# PREP head-prep phase: Q/K output stores staged through per-wave LDS and written as coalesced batches; norm gain vectors read from LDS instead of per-chunk global loads
# speedup vs baseline: 1.0284x; 1.0146x over previous
; DI void unpack8(u32x4 v, float* f) { f[0] = bflo(v.x); f[1] = bfhi(v.x); f[2] = bflo(v.y); f[3] = bfhi(v.y); f[4] = bflo(v.z); f[5] = bfhi(v.z); f[6] = bflo(v.w); f[7] = bfhi(v.w); }
; DI u32x4 pack8(const float* f) { u32x4 o; o.x = pk2(f[0], f[1]); o.y = pk2(f[2], f[3]); o.z = pk2(f[4], f[5]); o.w = pk2(f[6], f[7]); return o; }
; DI void prep_phase(const KArgs& a, int zz, int e, const bf16_t* Z, const bf16_t* QP, const bf16_t* KVP, bf16_t* Qb, bf16_t* Kb, bf16_t* VT, LAS unsigned char* lds, int G, int bid, int tid, int wave, int lane) {
;     const f32x2* taba = (const f32x2*)(a.ws + zz + OFF_TABA);
;     const float* qn_g = a.in[zz + 15] + e * 96; const float* kn_g = a.in[zz + 16] + e * 96;
;     const int gt = bid * NTHREADS + tid, GT = G * NTHREADS;
;     for (int gidx = gt; gidx < M * 8; gidx += GT) {
;     ...
;             for (int i = 0; i < 2; ++i) { float f2[8], o1[8], o2[8]; unpack8(kq[i], f); unpack8(kq[2 + i], f2);
; #pragma unroll
;                 for (int q = 0; q < 8; ++q) { const float x1 = f[q] * ks * kn_g[64 + i * 8 + q], x2 = f2[q] * ks * kn_g[80 + i * 8 + q];
;                     float c = 1.f, s = 0.f; if (lat) { const f32x2 cs = taba[t * 16 + i * 8 + q]; c = cs[0]; s = cs[1]; }
;                     o1[q] = x1 * c - x2 * s; o2[q] = x1 * s + x2 * c; }
;                 *(u32x4*)(dst + 64 + i * 8) = pack8(o1); *(u32x4*)(dst + 80 + i * 8) = pack8(o2); }
.LBB0_463:
	s_andn2_b64 vcc, exec, s[0:1]
	s_cbranch_vccnz .LBB0_544
	s_mov_b32 s0, 0x88000
	v_cmp_gt_i32_e32 vcc, s0, v154
	s_and_saveexec_b64 s[0:1], vcc
	s_cbranch_execz .LBB0_535
	s_add_u32 s6, s84, 0x2dfdc000
	s_addc_u32 s7, s85, 0
	s_add_u32 s8, s84, 0x345dc000
	s_addc_u32 s9, s85, 0
	s_add_u32 s38, s84, 0x6a58000
	s_addc_u32 s39, s85, 0
	s_lshl_b64 s[4:5], s[78:79], 3
	v_readlane_b32 s12, v253, 5
	v_readlane_b32 s13, v253, 6
	s_add_u32 s4, s12, s4
	s_addc_u32 s5, s13, s5
	s_load_dwordx4 s[24:27], s[4:5], 0x78
	v_and_b32_e32 v153, 7, v153
	v_readlane_b32 s4, v253, 9
	s_waitcnt vmcnt(5)
	v_mul_u32_u24_e32 v1, 0x60, v153
	v_readlane_b32 s5, v253, 10
	v_lshlrev_b32_e32 v148, 1, v1
	v_xor_b32_e32 v1, 1, v210
	s_and_b64 s[4:5], s[4:5], exec
	v_cmp_lt_i32_e32 vcc, v1, v250
	s_cselect_b32 s4, 0x180, 0
	s_waitcnt lgkmcnt(0)
	s_add_u32 s40, s24, s4
	v_cndmask_b32_e32 v1, v210, v1, vcc
	v_lshlrev_b32_e32 v155, 2, v1
	v_xor_b32_e32 v1, 2, v210
	s_addc_u32 s41, s25, 0
	v_cmp_lt_i32_e32 vcc, v1, v250
	s_add_u32 s42, s26, s4
	s_waitcnt vmcnt(4)
	v_lshl_add_u64 v[4:5], s[84:85], 0, v[148:149]
	s_mov_b64 s[4:5], 0x246dc000
	v_lshlrev_b32_e32 v148, 8, v153
	v_cndmask_b32_e32 v1, v210, v1, vcc
	v_cmp_lt_i32_e32 vcc, v251, v250
	v_lshlrev_b32_e32 v0, 5, v153
	v_lshlrev_b32_e32 v2, 4, v153
	v_lshl_add_u64 v[32:33], v[4:5], 0, s[4:5]
	v_lshl_add_u64 v[4:5], s[84:85], 0, v[148:149]
	s_mov_b64 s[4:5], 0x1bedc000
	v_lshlrev_b32_e32 v164, 2, v1
	v_cndmask_b32_e32 v1, v210, v251, vcc
	s_addc_u32 s43, s27, 0
	v_lshl_add_u64 v[34:35], v[4:5], 0, s[4:5]
	v_lshlrev_b32_e32 v165, 2, v1
	s_mov_b64 s[44:45], 0
	v_lshlrev_b32_e32 v148, 1, v0
	v_lshlrev_b32_e32 v36, 1, v2
	v_and_b32_e32 v245, 7, v152
	v_lshrrev_b32_e32 v246, 3, v152
	s_lshl_b32 s100, s37, 14
	v_mov_b32_e32 v247, 0x610
	v_mul_u32_u24_e32 v238, v245, v247
	v_mul_u32_u24_e32 v248, 0xc0, v246
	v_lshlrev_b32_e32 v242, 4, v152
	v_add3_u32 v238, v238, v248, s100
	v_add_u32_e32 v239, s100, v242
	v_add_u32_e32 v248, 0x400, v242
	v_add_u32_e32 v249, 0x410, v242
	v_add_u32_e32 v241, 0x810, v242
	v_add_u32_e32 v244, 0xcc200, v242
	v_add_u32_e32 v241, s100, v241
	v_add_u32_e32 v247, 0xcbe00, v242
	s_nop 1
	v_cmp_gt_u32_e64 s[100:101], 32, v152
	s_nop 3
	v_cndmask_b32_e64 v240, v249, v248, s[100:101]
	v_cndmask_b32_e64 v243, v247, v248, s[100:101]
	s_lshl_b32 s100, s37, 14
	s_nop 0
	v_add_u32_e32 v240, s100, v240
	v_min_u32_e32 v208, 23, v152
	v_lshlrev_b32_e32 v208, 4, v208
	s_lshl_b32 s100, s37, 14
	s_add_i32 s100, s100, 0x3100
	global_load_dwordx4 v[184:187], v208, s[40:41]
	global_load_dwordx4 v[188:191], v208, s[42:43]
	v_mov_b32_e32 v209, s100
	v_add_u32_e32 v208, s100, v208
	s_waitcnt vmcnt(0)
	ds_write_b128 v208, v[184:187]
	ds_write_b128 v208, v[188:191] offset:384
	s_branch .LBB0_467
.LBB0_466:
	s_or_b64 exec, exec, s[4:5]
	v_mul_f32_e32 v31, v10, v31
	v_mul_f32_e32 v37, v10, v117
	s_waitcnt vmcnt(1) lgkmcnt(0)
	v_mul_f32_e32 v31, v31, v49
	v_mul_f32_e32 v37, v37, v50
	v_mul_f32_e32 v49, v31, v19
	v_mov_b32_e32 v11, v10
	v_fma_f32 v49, v37, v18, -v49
	v_mul_f32_e32 v37, v37, v19
	v_fmac_f32_e32 v37, v31, v18
	v_pk_mul_f32 v[18:19], v[10:11], v[38:39]
	v_mul_f32_e32 v11, v10, v116
	s_waitcnt vmcnt(0)
	v_pk_mul_f32 v[18:19], v[18:19], v[20:21]
	v_mul_f32_e32 v20, v10, v28
	v_mul_f32_e32 v20, v20, v47
	v_mul_f32_e32 v11, v11, v48
	v_mul_f32_e32 v21, v20, v17
	v_fma_f32 v21, v11, v16, -v21
	v_mul_f32_e32 v11, v11, v17
	v_mul_f32_e32 v17, v10, v29
	v_fmac_f32_e32 v11, v20, v16
	v_mul_f32_e32 v16, v10, v115
	v_mul_f32_e32 v17, v17, v45
	v_mul_f32_e32 v16, v16, v46
	v_mul_f32_e32 v20, v17, v13
	v_fma_f32 v20, v16, v12, -v20
	v_mul_f32_e32 v13, v16, v13
	v_mul_f32_e32 v16, v10, v24
	v_fmac_f32_e32 v13, v17, v12
	v_mul_f32_e32 v12, v10, v114
	v_mul_f32_e32 v16, v16, v43
	v_mul_f32_e32 v12, v12, v44
	v_mul_f32_e32 v17, v16, v7
	v_fma_f32 v17, v12, v6, -v17
	v_mul_f32_e32 v7, v12, v7
	v_mul_f32_e32 v12, v10, v25
	v_fmac_f32_e32 v7, v16, v6
	v_mul_f32_e32 v6, v10, v113
	v_mul_f32_e32 v12, v12, v41
	v_mul_f32_e32 v6, v6, v42
	v_mul_f32_e32 v16, v12, v5
	v_fma_f32 v16, v6, v4, -v16
	v_mul_f32_e32 v6, v6, v5
	v_fmac_f32_e32 v6, v12, v4
	v_mul_f32_e32 v4, v10, v112
	v_mul_f32_e32 v5, v10, v22
	v_mul_f32_e32 v4, v4, v40
	v_mul_f32_e32 v5, v5, v30
	v_mul_f32_e32 v12, v5, v3
	v_mul_f32_e32 v22, v4, v3
	v_fma_f32 v12, v4, v2, -v12
	v_fmac_f32_e32 v22, v5, v2
	v_mul_f32_e32 v2, v10, v111
	v_mul_f32_e32 v3, v10, v23
	v_mul_f32_e32 v2, v2, v27
	v_mul_f32_e32 v3, v3, v26
	v_mul_f32_e32 v4, v3, v1
	v_mul_f32_e32 v23, v2, v1
	v_fma_f32 v10, v2, v0, -v4
	v_fmac_f32_e32 v23, v3, v0
	v_mul_f32_e32 v0, v18, v14
	v_pk_fma_f32 v[2:3], v[18:19], v[14:15], v[0:1] op_sel_hi:[1,1,0] neg_lo:[1,0,0] neg_hi:[1,0,0]
	v_mul_f32_e32 v0, v19, v14
	v_add_u32_e32 v154, s86, v154
	s_mov_b32 s4, 0x87fff
	v_pk_fma_f32 v[4:5], v[18:19], v[14:15], v[0:1] op_sel:[1,0,0] op_sel_hi:[0,1,0]
	v_cvt_pk_bf16_f32 v0, v10, v12
	v_cvt_pk_bf16_f32 v1, v16, v17
	v_cvt_pk_bf16_f32 v2, v20, v21
	v_cvt_pk_bf16_f32 v3, v49, v3
	v_cmp_lt_i32_e32 vcc, s4, v154
	ds_write_b128 v238, v[0:3] offset:144
	s_or_b64 s[44:45], vcc, s[44:45]
	s_nop 0
	v_cvt_pk_bf16_f32 v0, v23, v22
	v_cvt_pk_bf16_f32 v1, v6, v7
	v_cvt_pk_bf16_f32 v2, v13, v11
	v_cvt_pk_bf16_f32 v3, v37, v5
	ds_write_b128 v238, v[0:3] offset:176
	v_readfirstlane_b32 s98, v8
	v_readfirstlane_b32 s99, v9
	s_waitcnt lgkmcnt(0)
	ds_read_b128 v[184:187], v239
	ds_read_b128 v[188:191], v240
	ds_read_b128 v[192:195], v241
	ds_read_b128 v[196:199], v239 offset:3104
	ds_read_b128 v[200:203], v240 offset:3104
	ds_read_b128 v[204:207], v241 offset:3104
	ds_read_b128 v[214:217], v239 offset:6208
	ds_read_b128 v[218:221], v240 offset:6208
	ds_read_b128 v[222:225], v241 offset:6208
	ds_read_b128 v[226:229], v239 offset:9312
	ds_read_b128 v[230:233], v240 offset:9312
	ds_read_b128 v[234:237], v241 offset:9312
	s_waitcnt lgkmcnt(9)
	global_store_dwordx4 v242, v[184:187], s[98:99]
	global_store_dwordx4 v243, v[188:191], s[98:99]
	global_store_dwordx4 v244, v[192:195], s[98:99]
	s_add_u32 s98, s98, 0x198000
	s_addc_u32 s99, s99, 0
	s_waitcnt lgkmcnt(6)
	global_store_dwordx4 v242, v[196:199], s[98:99]
	global_store_dwordx4 v243, v[200:203], s[98:99]
	global_store_dwordx4 v244, v[204:207], s[98:99]
	s_add_u32 s98, s98, 0x198000
	s_addc_u32 s99, s99, 0
	s_waitcnt lgkmcnt(3)
	global_store_dwordx4 v242, v[214:217], s[98:99]
	global_store_dwordx4 v243, v[218:221], s[98:99]
	global_store_dwordx4 v244, v[222:225], s[98:99]
	s_add_u32 s98, s98, 0x198000
	s_addc_u32 s99, s99, 0
	s_waitcnt lgkmcnt(0)
	global_store_dwordx4 v242, v[226:229], s[98:99]
	global_store_dwordx4 v243, v[230:233], s[98:99]
	global_store_dwordx4 v244, v[234:237], s[98:99]
	s_andn2_b64 exec, exec, s[44:45]
	s_cbranch_execz .LBB0_535
; DI void unpack8(u32x4 v, float* f) { f[0] = bflo(v.x); f[1] = bfhi(v.x); f[2] = bflo(v.y); f[3] = bfhi(v.y); f[4] = bflo(v.z); f[5] = bfhi(v.z); f[6] = bflo(v.w); f[7] = bfhi(v.w); }
; DI void prep_phase(const KArgs& a, int zz, int e, const bf16_t* Z, const bf16_t* QP, const bf16_t* KVP, bf16_t* Qb, bf16_t* Kb, bf16_t* VT, LAS unsigned char* lds, int G, int bid, int tid, int wave, int lane) {
;     ...
;     for (int gidx = gt; gidx < M * 8; gidx += GT) {
;         const int row = gidx >> 3, h = gidx & 7;
;         const bool lat = row < ML; int b, pos, t = 0;
;         if (lat) { b = row >> 12; t = row & 4095; pos = TC + t; } else { const int rc = row - ML; b = rc >> 8; pos = rc & 255; }
;         const bf16_t* zr = Z + (size_t)row * ZW;
;         float f[8];
;         float ss = 0.f;
; #pragma unroll
;         for (int i = 0; i < 4; ++i) { unpack8(*(const u32x4*)(zr + h * 32 + i * 8), f);
; #pragma unroll
;             for (int q = 0; q < 8; ++q) ss += f[q] * f[q]; }
;         ss += __shfl_xor(ss, 1); ss += __shfl_xor(ss, 2); ss += __shfl_xor(ss, 4);
;         const float rs_q = rsqrtf(ss * (1.f / 256.f) + EPS);
;         ss = 0.f;
; #pragma unroll
;         for (int i = 0; i < 2; ++i) { unpack8(*(const u32x4*)(zr + 256 + h * 16 + i * 8), f);
; #pragma unroll
;             for (int q = 0; q < 8; ++q) ss += f[q] * f[q]; }
;         ss += __shfl_xor(ss, 1); ss += __shfl_xor(ss, 2); ss += __shfl_xor(ss, 4);
;         const float rs_kv = rsqrtf(ss * (1.f / 128.f) + EPS);
.LBB0_467:
	v_ashrrev_i32_e32 v38, 3, v154
	s_mov_b32 s4, 0x10000
	v_cmp_gt_i32_e32 vcc, s4, v38
	s_mov_b32 s4, 0xffff
	v_cmp_lt_i32_e64 s[4:5], s4, v38
	s_and_saveexec_b64 s[24:25], s[4:5]
	s_xor_b64 s[4:5], exec, s[24:25]
	v_add_u32_e32 v0, 0xffff0000, v38
	v_lshrrev_b32_e32 v51, 8, v0
	v_bfe_u32 v62, v154, 3, 8
	s_or_saveexec_b64 s[4:5], s[4:5]
	v_mov_b32_e32 v45, 0
	v_mov_b32_e32 v39, 0
	s_xor_b64 exec, exec, s[4:5]
	v_bfe_u32 v0, v154, 3, 12
	v_ashrrev_i32_e32 v51, 15, v154
	v_add_u32_e32 v62, 0x100, v0
	v_lshlrev_b32_e32 v39, 4, v0
	s_or_b64 exec, exec, s[4:5]
	s_movk_i32 s4, 0x600
	v_mov_b64_e32 v[0:1], s[80:81]
	v_mad_i64_i32 v[42:43], s[4:5], v38, s4, v[32:33]
	v_mad_i64_i32 v[40:41], s[4:5], v38, s64, v[0:1]
	v_lshl_add_u64 v[0:1], v[40:41], 0, v[148:149]
	global_load_dwordx4 v[86:89], v[42:43], off offset:128
	global_load_dwordx4 v[90:93], v[42:43], off offset:144
	global_load_dwordx4 v[46:49], v[0:1], off
	global_load_dwordx4 v[58:61], v[0:1], off offset:16
	global_load_dwordx4 v[64:67], v[0:1], off offset:32
	global_load_dwordx4 v[68:71], v[0:1], off offset:48
	v_mov_b32_e32 v37, v149
	v_lshl_add_u64 v[52:53], v[40:41], 0, v[36:37]
	global_load_dwordx4 v[76:79], v[52:53], off offset:512
	global_load_dwordx4 v[20:23], v[42:43], off offset:48
	global_load_dwordx4 v[24:27], v[42:43], off offset:32
	global_load_dwordx4 v[28:31], v[42:43], off offset:16
	global_load_dwordx4 v[110:113], v[42:43], off
	global_load_dwordx4 v[4:7], v[42:43], off offset:112
	global_load_dwordx4 v[8:11], v[42:43], off offset:96
	global_load_dwordx4 v[12:15], v[42:43], off offset:80
	global_load_dwordx4 v[16:19], v[42:43], off offset:64
	global_load_dwordx4 v[0:3], v[42:43], off offset:176
	global_load_dwordx4 v[94:97], v[42:43], off offset:160
	global_load_dwordx4 v[80:83], v[52:53], off offset:528
	global_load_dwordx4 v[176:179], v149, s[40:41] offset:16
	global_load_dwordx4 v[180:183], v149, s[40:41]
	s_movk_i32 s12, 0x60
	s_waitcnt vmcnt(13)
	v_lshlrev_b32_e32 v73, 16, v76
	s_waitcnt vmcnt(12)
	v_lshlrev_b32_e32 v134, 16, v20
	s_waitcnt vmcnt(11)
	v_lshlrev_b32_e32 v122, 16, v24
	v_and_b32_e32 v123, 0xffff0000, v24
	v_and_b32_e32 v135, 0xffff0000, v20
	v_and_b32_e32 v44, 0xffff0000, v46
	v_lshlrev_b32_e32 v37, 16, v46
	v_mul_f32_e32 v44, v44, v44
	v_lshlrev_b32_e32 v50, 16, v47
	v_fmac_f32_e32 v44, v37, v37
	v_and_b32_e32 v56, 0xffff0000, v47
	v_fmac_f32_e32 v44, v50, v50
	v_lshlrev_b32_e32 v63, 16, v48
	v_fmac_f32_e32 v44, v56, v56
	v_and_b32_e32 v72, 0xffff0000, v48
	v_fmac_f32_e32 v44, v63, v63
	v_lshlrev_b32_e32 v74, 16, v49
	v_fmac_f32_e32 v44, v72, v72
	v_and_b32_e32 v75, 0xffff0000, v49
	v_fmac_f32_e32 v44, v74, v74
	v_lshlrev_b32_e32 v84, 16, v58
	v_fmac_f32_e32 v44, v75, v75
	v_and_b32_e32 v85, 0xffff0000, v58
	v_fmac_f32_e32 v44, v84, v84
	v_lshlrev_b32_e32 v167, 16, v86
	v_and_b32_e32 v168, 0xffff0000, v86
	v_lshlrev_b32_e32 v86, 16, v59
	v_fmac_f32_e32 v44, v85, v85
	v_and_b32_e32 v52, 0xffff0000, v87
	v_lshlrev_b32_e32 v53, 16, v87
	v_and_b32_e32 v87, 0xffff0000, v59
	v_fmac_f32_e32 v44, v86, v86
	v_and_b32_e32 v54, 0xffff0000, v88
	v_lshlrev_b32_e32 v55, 16, v88
	v_lshlrev_b32_e32 v88, 16, v60
	v_fmac_f32_e32 v44, v87, v87
	v_and_b32_e32 v42, 0xffff0000, v90
	v_lshlrev_b32_e32 v43, 16, v90
	v_and_b32_e32 v90, 0xffff0000, v60
	v_fmac_f32_e32 v44, v88, v88
	v_lshlrev_b32_e32 v98, 16, v61
	v_fmac_f32_e32 v44, v90, v90
	v_and_b32_e32 v99, 0xffff0000, v61
	v_fmac_f32_e32 v44, v98, v98
	v_lshlrev_b32_e32 v100, 16, v64
	v_fmac_f32_e32 v44, v99, v99
	v_and_b32_e32 v64, 0xffff0000, v64
	v_fmac_f32_e32 v44, v100, v100
	v_lshlrev_b32_e32 v101, 16, v65
	v_fmac_f32_e32 v44, v64, v64
	v_and_b32_e32 v102, 0xffff0000, v65
	v_fmac_f32_e32 v44, v101, v101
	v_lshlrev_b32_e32 v103, 16, v66
	v_fmac_f32_e32 v44, v102, v102
	v_and_b32_e32 v66, 0xffff0000, v66
	v_fmac_f32_e32 v44, v103, v103
	v_lshlrev_b32_e32 v104, 16, v67
	v_fmac_f32_e32 v44, v66, v66
	v_and_b32_e32 v105, 0xffff0000, v67
	v_and_b32_e32 v46, 0xffff0000, v68
	v_lshlrev_b32_e32 v47, 16, v68
	v_fmac_f32_e32 v44, v104, v104
	v_pk_mul_f32 v[46:47], v[46:47], v[46:47]
	v_fmac_f32_e32 v44, v105, v105
	v_and_b32_e32 v48, 0xffff0000, v69
	v_lshlrev_b32_e32 v49, 16, v69
	v_add_f32_e32 v37, v47, v44
	v_pk_mul_f32 v[48:49], v[48:49], v[48:49]
	v_add_f32_e32 v37, v46, v37
	v_and_b32_e32 v58, 0xffff0000, v70
	v_lshlrev_b32_e32 v59, 16, v70
	v_add_f32_e32 v37, v49, v37
	v_pk_mul_f32 v[58:59], v[58:59], v[58:59]
	v_add_f32_e32 v37, v48, v37
	v_and_b32_e32 v60, 0xffff0000, v71
	v_lshlrev_b32_e32 v61, 16, v71
	v_add_f32_e32 v37, v59, v37
	v_pk_mul_f32 v[60:61], v[60:61], v[60:61]
	v_add_f32_e32 v37, v58, v37
	v_add_f32_e32 v37, v61, v37
	v_add_f32_e32 v37, v60, v37
	ds_bpermute_b32 v44, v155, v37
	s_waitcnt vmcnt(2)
	v_and_b32_e32 v46, 0xffff0000, v80
	v_lshlrev_b32_e32 v47, 16, v80
	v_and_b32_e32 v48, 0xffff0000, v81
	v_lshlrev_b32_e32 v49, 16, v81
	s_waitcnt lgkmcnt(0)
	v_add_f32_e32 v37, v37, v44
	ds_bpermute_b32 v44, v164, v37
	v_and_b32_e32 v58, 0xffff0000, v82
	v_lshlrev_b32_e32 v59, 16, v82
	v_and_b32_e32 v60, 0xffff0000, v83
	v_lshlrev_b32_e32 v61, 16, v83
	s_waitcnt lgkmcnt(0)
	v_add_f32_e32 v37, v37, v44
	ds_bpermute_b32 v44, v165, v37
	v_pk_mul_f32 v[82:83], v[46:47], v[46:47]
	v_pk_mul_f32 v[84:85], v[48:49], v[48:49]
	v_pk_mul_f32 v[80:81], v[58:59], v[58:59]
	v_and_b32_e32 v101, 0xffff0000, v110
	s_waitcnt lgkmcnt(0)
; DI void unpack8(u32x4 v, float* f) { f[0] = bflo(v.x); f[1] = bfhi(v.x); f[2] = bflo(v.y); f[3] = bfhi(v.y); f[4] = bflo(v.z); f[5] = bfhi(v.z); f[6] = bflo(v.w); f[7] = bfhi(v.w); }
; DI void prep_phase(const KArgs& a, int zz, int e, const bf16_t* Z, const bf16_t* QP, const bf16_t* KVP, bf16_t* Qb, bf16_t* Kb, bf16_t* VT, LAS unsigned char* lds, int G, int bid, int tid, int wave, int lane) {
;     ...
;         const float rs_q = rsqrtf(ss * (1.f / 256.f) + EPS);
;         ss = 0.f;
; #pragma unroll
;         for (int i = 0; i < 2; ++i) { unpack8(*(const u32x4*)(zr + 256 + h * 16 + i * 8), f);
; #pragma unroll
;             for (int q = 0; q < 8; ++q) ss += f[q] * f[q]; }
;         ss += __shfl_xor(ss, 1); ss += __shfl_xor(ss, 2); ss += __shfl_xor(ss, 4);
;         const float rs_kv = rsqrtf(ss * (1.f / 128.f) + EPS);
;         {
;             const bf16_t* src = QP + (size_t)row * 768 + h * 96;
;             bf16_t* dst = Qb + ((size_t)(b * 8 + h) * TK + pos) * 96;
;             u32x4 qr[12];
; #pragma unroll
;             for (int i = 0; i < 12; ++i) qr[i] = *(const u32x4*)(src + i * 8);
;             float s2 = 0.f;
; #pragma unroll
;             for (int i = 0; i < 12; ++i) { unpack8(qr[i], f);
; #pragma unroll
;                 for (int q = 0; q < 8; ++q) { const float v = f[q] * rs_q; s2 += v * v; } }
	v_add_f32_e32 v37, v37, v44
	v_fmamk_f32 v37, v37, 0x3b800000, v150
	v_mul_f32_e32 v44, 0x4b800000, v37
	v_cmp_gt_f32_e64 s[4:5], s62, v37
	v_lshlrev_b32_e32 v65, 16, v77
	v_and_b32_e32 v71, 0xffff0000, v77
	v_cndmask_b32_e64 v37, v37, v44, s[4:5]
	v_rsq_f32_e32 v37, v37
	v_lshlrev_b32_e32 v69, 16, v78
	v_and_b32_e32 v67, 0xffff0000, v78
	v_lshlrev_b32_e32 v77, 16, v79
	v_mul_f32_e32 v44, 0x45800000, v37
	v_cndmask_b32_e64 v44, v37, v44, s[4:5]
	v_pk_mul_f32 v[46:47], v[44:45], v[52:53] op_sel_hi:[0,1]
	v_pk_mul_f32 v[48:49], v[44:45], v[54:55] op_sel_hi:[0,1]
	v_pk_mul_f32 v[118:119], v[46:47], v[46:47]
	v_and_b32_e32 v46, 0xffff0000, v91
	v_lshlrev_b32_e32 v47, 16, v91
	v_pk_mul_f32 v[114:115], v[48:49], v[48:49]
	v_pk_mul_f32 v[48:49], v[44:45], v[46:47] op_sel_hi:[0,1]
	v_pk_mul_f32 v[58:59], v[44:45], v[42:43] op_sel_hi:[0,1]
	v_pk_mul_f32 v[106:107], v[48:49], v[48:49]
	v_and_b32_e32 v48, 0xffff0000, v92
	v_lshlrev_b32_e32 v49, 16, v92
	v_pk_mul_f32 v[104:105], v[58:59], v[58:59]
	v_pk_mul_f32 v[58:59], v[44:45], v[48:49] op_sel_hi:[0,1]
	v_and_b32_e32 v75, 0xffff0000, v79
	v_pk_mul_f32 v[78:79], v[60:61], v[60:61]
	v_pk_mul_f32 v[108:109], v[58:59], v[58:59]
	v_lshlrev_b32_e32 v61, 16, v97
	v_and_b32_e32 v59, 0xffff0000, v97
	v_lshlrev_b32_e32 v100, 16, v110
	v_mul_f32_e32 v97, v44, v101
	v_lshlrev_b32_e32 v169, 16, v94
	v_and_b32_e32 v170, 0xffff0000, v94
	v_lshlrev_b32_e32 v173, 16, v96
	v_and_b32_e32 v174, 0xffff0000, v96
	v_lshlrev_b32_e32 v94, 16, v111
	v_mul_f32_e32 v96, v44, v100
	v_mul_f32_e32 v99, v97, v97
	v_lshlrev_b32_e32 v171, 16, v95
	v_and_b32_e32 v172, 0xffff0000, v95
	v_mul_f32_e32 v50, v44, v174
	v_and_b32_e32 v58, 0xffff0000, v89
	v_and_b32_e32 v95, 0xffff0000, v111
	v_mul_f32_e32 v92, v44, v94
	v_fmac_f32_e32 v99, v96, v96
	v_lshlrev_b32_e32 v57, 16, v89
	v_lshlrev_b32_e32 v166, 16, v93
	v_mul_f32_e32 v98, v50, v50
	v_mov_b32_e32 v56, v58
	v_and_b32_e32 v50, 0xffff0000, v93
	v_lshlrev_b32_e32 v90, 16, v112
	v_mul_f32_e32 v93, v44, v95
	v_fmac_f32_e32 v99, v92, v92
	v_pk_mul_f32 v[88:89], v[44:45], v[56:57] op_sel_hi:[0,1]
	v_and_b32_e32 v91, 0xffff0000, v112
	v_mul_f32_e32 v64, v44, v90
	v_fmac_f32_e32 v99, v93, v93
	v_pk_mul_f32 v[156:157], v[88:89], v[88:89]
	v_lshlrev_b32_e32 v88, 16, v113
	v_mul_f32_e32 v86, v44, v91
	v_fmac_f32_e32 v99, v64, v64
	v_mov_b32_e32 v60, v59
	v_and_b32_e32 v89, 0xffff0000, v113
	v_mul_f32_e32 v56, v44, v88
	v_fmac_f32_e32 v99, v86, v86
	v_pk_mul_f32 v[160:161], v[44:45], v[60:61] op_sel_hi:[0,1]
	v_mul_f32_e32 v60, v44, v89
	v_fmac_f32_e32 v99, v56, v56
	v_lshlrev_b32_e32 v112, 16, v28
	v_fmac_f32_e32 v99, v60, v60
	v_and_b32_e32 v113, 0xffff0000, v28
	v_mul_f32_e32 v28, v44, v112
	v_lshlrev_b32_e32 v96, 16, v30
	v_and_b32_e32 v97, 0xffff0000, v30
	v_lshlrev_b32_e32 v30, 16, v29
	v_mul_f32_e32 v103, v44, v113
	v_fmac_f32_e32 v99, v28, v28
	v_lshlrev_b32_e32 v92, 16, v31
	v_and_b32_e32 v93, 0xffff0000, v31
	v_and_b32_e32 v31, 0xffff0000, v29
	v_mul_f32_e32 v29, v44, v30
	v_fmac_f32_e32 v99, v103, v103
	v_mul_f32_e32 v102, v44, v31
	v_fmac_f32_e32 v99, v29, v29
	v_mul_f32_e32 v64, v44, v96
	v_fmac_f32_e32 v99, v102, v102
	v_mul_f32_e32 v86, v44, v97
	v_fmac_f32_e32 v99, v64, v64
	v_mul_f32_e32 v56, v44, v92
	v_fmac_f32_e32 v99, v86, v86
	v_mul_f32_e32 v60, v44, v93
	v_fmac_f32_e32 v99, v56, v56
	v_fmac_f32_e32 v99, v60, v60
	v_mul_f32_e32 v24, v44, v122
	v_lshlrev_b32_e32 v102, 16, v26
	v_and_b32_e32 v103, 0xffff0000, v26
	v_lshlrev_b32_e32 v26, 16, v25
	v_mul_f32_e32 v111, v44, v123
	v_fmac_f32_e32 v99, v24, v24
	v_lshlrev_b32_e32 v28, 16, v27
	v_and_b32_e32 v29, 0xffff0000, v27
	v_and_b32_e32 v27, 0xffff0000, v25
	v_mul_f32_e32 v25, v44, v26
	v_fmac_f32_e32 v99, v111, v111
	v_mul_f32_e32 v110, v44, v27
	v_fmac_f32_e32 v99, v25, v25
	v_mul_f32_e32 v64, v44, v102
	v_fmac_f32_e32 v99, v110, v110
	v_mul_f32_e32 v86, v44, v103
	v_fmac_f32_e32 v99, v64, v64
	v_mul_f32_e32 v56, v44, v28
	v_fmac_f32_e32 v99, v86, v86
	v_mul_f32_e32 v60, v44, v29
	v_fmac_f32_e32 v99, v56, v56
	v_fmac_f32_e32 v99, v60, v60
	v_mul_f32_e32 v20, v44, v134
	v_lshlrev_b32_e32 v120, 16, v21
	v_mul_f32_e32 v86, v44, v135
	v_fmac_f32_e32 v99, v20, v20
	v_and_b32_e32 v121, 0xffff0000, v21
	v_mul_f32_e32 v21, v44, v120
	v_fmac_f32_e32 v99, v86, v86
	v_lshlrev_b32_e32 v110, 16, v22
	v_mul_f32_e32 v64, v44, v121
	v_fmac_f32_e32 v99, v21, v21
	v_and_b32_e32 v111, 0xffff0000, v22
	v_mul_f32_e32 v22, v44, v110
	v_fmac_f32_e32 v99, v64, v64
	v_lshlrev_b32_e32 v24, 16, v23
	v_mul_f32_e32 v60, v44, v111
	v_fmac_f32_e32 v99, v22, v22
	v_and_b32_e32 v25, 0xffff0000, v23
	v_mul_f32_e32 v23, v44, v24
	v_fmac_f32_e32 v99, v60, v60
	v_mul_f32_e32 v56, v44, v25
	v_fmac_f32_e32 v99, v23, v23
	v_lshlrev_b32_e32 v138, 16, v16
	v_fmac_f32_e32 v99, v56, v56
	v_and_b32_e32 v139, 0xffff0000, v16
	v_mul_f32_e32 v16, v44, v138
	v_lshlrev_b32_e32 v126, 16, v17
	v_mul_f32_e32 v60, v44, v139
	v_fmac_f32_e32 v99, v16, v16
	v_and_b32_e32 v127, 0xffff0000, v17
	v_mul_f32_e32 v17, v44, v126
	v_fmac_f32_e32 v99, v60, v60
	v_lshlrev_b32_e32 v116, 16, v18
	v_mul_f32_e32 v56, v44, v127
	v_fmac_f32_e32 v99, v17, v17
	v_and_b32_e32 v117, 0xffff0000, v18
	v_mul_f32_e32 v18, v44, v116
	v_fmac_f32_e32 v99, v56, v56
	v_lshlrev_b32_e32 v22, 16, v19
	v_mul_f32_e32 v21, v44, v117
	v_fmac_f32_e32 v99, v18, v18
	v_and_b32_e32 v23, 0xffff0000, v19
	v_mul_f32_e32 v19, v44, v22
	v_fmac_f32_e32 v99, v21, v21
	v_mul_f32_e32 v20, v44, v23
	v_fmac_f32_e32 v99, v19, v19
	v_lshlrev_b32_e32 v142, 16, v12
	v_fmac_f32_e32 v99, v20, v20
	v_and_b32_e32 v143, 0xffff0000, v12
	v_mul_f32_e32 v12, v44, v142
	v_lshlrev_b32_e32 v130, 16, v13
	v_mul_f32_e32 v60, v44, v143
; DI void unpack8(u32x4 v, float* f) { f[0] = bflo(v.x); f[1] = bfhi(v.x); f[2] = bflo(v.y); f[3] = bfhi(v.y); f[4] = bflo(v.z); f[5] = bfhi(v.z); f[6] = bflo(v.w); f[7] = bfhi(v.w); }
; DI void prep_phase(const KArgs& a, int zz, int e, const bf16_t* Z, const bf16_t* QP, const bf16_t* KVP, bf16_t* Qb, bf16_t* Kb, bf16_t* VT, LAS unsigned char* lds, int G, int bid, int tid, int wave, int lane) {
;     ...
;         for (int i = 0; i < 2; ++i) { unpack8(*(const u32x4*)(zr + 256 + h * 16 + i * 8), f);
; #pragma unroll
;             for (int q = 0; q < 8; ++q) ss += f[q] * f[q]; }
;         ss += __shfl_xor(ss, 1); ss += __shfl_xor(ss, 2); ss += __shfl_xor(ss, 4);
;         const float rs_kv = rsqrtf(ss * (1.f / 128.f) + EPS);
;         {
;             const bf16_t* src = QP + (size_t)row * 768 + h * 96;
;             bf16_t* dst = Qb + ((size_t)(b * 8 + h) * TK + pos) * 96;
;             u32x4 qr[12];
; #pragma unroll
;             for (int i = 0; i < 12; ++i) qr[i] = *(const u32x4*)(src + i * 8);
;             float s2 = 0.f;
; #pragma unroll
;             for (int i = 0; i < 12; ++i) { unpack8(qr[i], f);
; #pragma unroll
;                 for (int q = 0; q < 8; ++q) { const float v = f[q] * rs_q; s2 += v * v; } }
;             const float fs = rs_q * rsqrtf(s2 * (1.f / 96.f) + EPS);
; #pragma unroll
;             for (int i = 0; i < 8; ++i) { unpack8(qr[i], f); float o[8];
; #pragma unroll
;                 for (int q = 0; q < 8; ++q) o[q] = f[q] * fs * qn_g[i * 8 + q] * QSCALE;
	v_fmac_f32_e32 v99, v12, v12
	v_and_b32_e32 v131, 0xffff0000, v13
	v_mul_f32_e32 v13, v44, v130
	v_fmac_f32_e32 v99, v60, v60
	v_lshlrev_b32_e32 v18, 16, v14
	v_mul_f32_e32 v56, v44, v131
	v_fmac_f32_e32 v99, v13, v13
	v_and_b32_e32 v19, 0xffff0000, v14
	v_mul_f32_e32 v14, v44, v18
	v_fmac_f32_e32 v99, v56, v56
	v_lshlrev_b32_e32 v16, 16, v15
	v_mul_f32_e32 v21, v44, v19
	v_fmac_f32_e32 v99, v14, v14
	v_and_b32_e32 v17, 0xffff0000, v15
	v_mul_f32_e32 v15, v44, v16
	v_fmac_f32_e32 v99, v21, v21
	v_mul_f32_e32 v20, v44, v17
	v_fmac_f32_e32 v99, v15, v15
	v_lshlrev_b32_e32 v158, 16, v8
	v_fmac_f32_e32 v99, v20, v20
	v_and_b32_e32 v159, 0xffff0000, v8
	v_mul_f32_e32 v20, v44, v158
	v_lshlrev_b32_e32 v136, 16, v9
	v_mul_f32_e32 v21, v44, v159
	v_fmac_f32_e32 v99, v20, v20
	v_and_b32_e32 v137, 0xffff0000, v9
	v_mul_f32_e32 v8, v44, v136
	v_fmac_f32_e32 v99, v21, v21
	v_lshlrev_b32_e32 v128, 16, v10
	v_mul_f32_e32 v9, v44, v137
	v_fmac_f32_e32 v99, v8, v8
	v_and_b32_e32 v129, 0xffff0000, v10
	v_mul_f32_e32 v10, v44, v128
	v_fmac_f32_e32 v99, v9, v9
	v_lshlrev_b32_e32 v14, 16, v11
	v_mul_f32_e32 v13, v44, v129
	v_fmac_f32_e32 v99, v10, v10
	v_and_b32_e32 v15, 0xffff0000, v11
	v_mul_f32_e32 v11, v44, v14
	v_fmac_f32_e32 v99, v13, v13
	v_mul_f32_e32 v12, v44, v15
	v_fmac_f32_e32 v99, v11, v11
	v_lshlrev_b32_e32 v162, 16, v4
	v_fmac_f32_e32 v99, v12, v12
	v_lshlrev_b32_e32 v124, 16, v7
	v_and_b32_e32 v125, 0xffff0000, v7
	v_and_b32_e32 v163, 0xffff0000, v4
	v_mul_f32_e32 v7, v44, v162
	v_lshlrev_b32_e32 v140, 16, v5
	v_fmac_f32_e32 v99, v7, v7
	v_mul_f32_e32 v7, v44, v163
	v_and_b32_e32 v141, 0xffff0000, v5
	v_fmac_f32_e32 v99, v7, v7
	v_mul_f32_e32 v7, v44, v140
	v_lshlrev_b32_e32 v132, 16, v6
	v_fmac_f32_e32 v99, v7, v7
	v_mul_f32_e32 v7, v44, v141
	v_and_b32_e32 v133, 0xffff0000, v6
	v_mul_f32_e32 v6, v44, v132
	v_fmac_f32_e32 v99, v7, v7
	v_mul_f32_e32 v7, v44, v133
	v_fmac_f32_e32 v99, v6, v6
	v_mul_f32_e32 v4, v44, v124
	v_fmac_f32_e32 v99, v7, v7
	v_mul_f32_e32 v5, v44, v125
	v_fmac_f32_e32 v99, v4, v4
	v_mul_f32_e32 v37, v44, v167
	v_fmac_f32_e32 v99, v5, v5
	v_mul_f32_e32 v63, v44, v168
	v_fmac_f32_e32 v99, v37, v37
	v_fmac_f32_e32 v99, v63, v63
	v_add_f32_e32 v4, v119, v99
	v_add_f32_e32 v4, v118, v4
	v_add_f32_e32 v4, v115, v4
	v_add_f32_e32 v6, v114, v4
	v_and_b32_e32 v4, 0xffff0000, v0
	v_lshlrev_b32_e32 v5, 16, v0
	v_add_f32_e32 v0, v157, v6
	v_add_f32_e32 v0, v156, v0
	v_add_f32_e32 v0, v105, v0
	v_add_f32_e32 v0, v104, v0
	v_add_f32_e32 v0, v107, v0
	v_add_f32_e32 v8, v106, v0
	v_and_b32_e32 v68, 0xffff0000, v76
	v_add_f32_e32 v8, v109, v8
	v_mul_f32_e32 v87, v68, v68
	v_mul_f32_e32 v72, v44, v166
	v_add_f32_e32 v86, v108, v8
	v_pk_fma_f32 v[20:21], v[72:73], v[72:73], v[86:87]
	v_mul_f32_e32 v64, v44, v50
	v_mul_f32_e32 v70, v44, v169
	v_pk_fma_f32 v[20:21], v[64:65], v[64:65], v[20:21]
	v_mul_f32_e32 v68, v44, v170
	v_pk_fma_f32 v[20:21], v[70:71], v[70:71], v[20:21]
	v_mul_f32_e32 v66, v44, v171
	v_pk_fma_f32 v[20:21], v[68:69], v[68:69], v[20:21]
	v_mul_f32_e32 v76, v44, v172
	v_pk_fma_f32 v[20:21], v[66:67], v[66:67], v[20:21]
	v_mul_f32_e32 v74, v44, v173
	v_pk_fma_f32 v[20:21], v[76:77], v[76:77], v[20:21]
	v_pk_mul_f32 v[10:11], v[160:161], v[160:161]
	v_pk_fma_f32 v[20:21], v[74:75], v[74:75], v[20:21]
	v_mov_b32_e32 v99, v83
	v_pk_mul_f32 v[6:7], v[44:45], v[4:5] op_sel_hi:[0,1]
	v_pk_add_f32 v[20:21], v[98:99], v[20:21]
	v_pk_mov_b32 v[64:65], v[10:11], v[82:83] op_sel:[1,0]
	v_pk_mul_f32 v[12:13], v[6:7], v[6:7]
	v_and_b32_e32 v6, 0xffff0000, v1
	v_lshlrev_b32_e32 v7, 16, v1
	v_pk_add_f32 v[20:21], v[64:65], v[20:21]
	v_mov_b32_e32 v11, v85
	v_pk_mul_f32 v[0:1], v[44:45], v[6:7] op_sel_hi:[0,1]
	v_pk_add_f32 v[10:11], v[10:11], v[20:21]
	v_pk_mov_b32 v[20:21], v[12:13], v[84:85] op_sel:[1,0]
	v_pk_mul_f32 v[0:1], v[0:1], v[0:1]
	v_and_b32_e32 v8, 0xffff0000, v2
	v_lshlrev_b32_e32 v9, 16, v2
	v_pk_add_f32 v[10:11], v[20:21], v[10:11]
	v_mov_b32_e32 v13, v81
	v_pk_mul_f32 v[72:73], v[44:45], v[8:9] op_sel_hi:[0,1]
	v_pk_add_f32 v[10:11], v[12:13], v[10:11]
	v_pk_mov_b32 v[12:13], v[0:1], v[80:81] op_sel:[1,0]
	v_pk_mul_f32 v[72:73], v[72:73], v[72:73]
	v_pk_add_f32 v[10:11], v[12:13], v[10:11]
	v_mov_b32_e32 v1, v79
	v_pk_add_f32 v[0:1], v[0:1], v[10:11]
	v_pk_mov_b32 v[10:11], v[72:73], v[78:79] op_sel:[1,0]
	v_lshl_or_b32 v20, v51, 3, v153
	v_pk_add_f32 v[0:1], v[10:11], v[0:1]
	ds_bpermute_b32 v73, v155, v1
	v_lshlrev_b32_e32 v13, 16, v3
	v_and_b32_e32 v51, 0xffff0000, v3
	v_mov_b32_e32 v12, v51
	v_pk_mul_f32 v[10:11], v[44:45], v[12:13] op_sel_hi:[0,1]
	s_waitcnt lgkmcnt(0)
	v_pk_add_f32 v[0:1], v[72:73], v[0:1]
	ds_bpermute_b32 v3, v164, v1
	v_pk_mul_f32 v[10:11], v[10:11], v[10:11]
	v_mov_b32_e32 v63, v149
	v_mov_b32_e32 v2, v11
	s_movk_i32 s4, 0x1100
	s_waitcnt lgkmcnt(0)
	v_pk_add_f32 v[0:1], v[2:3], v[0:1]
	ds_bpermute_b32 v11, v165, v1
	v_mad_i64_i32 v[2:3], s[4:5], v20, s4, v[62:63]
	v_mad_u64_u32 v[20:21], s[4:5], v2, s12, 0
	s_mov_b32 s4, 0x3c2aaaab
	s_waitcnt lgkmcnt(0)
	v_pk_add_f32 v[0:1], v[10:11], v[0:1]
	s_brev_b32 s5, 60
	v_pk_fma_f32 v[0:1], v[0:1], s[4:5], v[150:151] op_sel_hi:[1,1,0]
	v_mov_b32_e32 v2, v21
	v_mul_f32_e32 v10, 0x4b800000, v0
	v_cmp_gt_f32_e64 s[4:5], s62, v0
	v_mad_u64_u32 v[2:3], s[24:25], v3, s12, v[2:3]
	s_nop 0
	v_cndmask_b32_e64 v0, v0, v10, s[4:5]
	v_rsq_f32_e32 v0, v0
	v_mov_b32_e32 v21, v2
	v_lshl_add_u64 v[2:3], v[20:21], 1, s[6:7]
	v_lshlrev_b32_e32 v37, 3, v39
	v_mul_f32_e32 v10, 0x45800000, v0
	v_cndmask_b32_e64 v0, v0, v10, s[4:5]
	v_mul_f32_e32 v10, v44, v0
	v_pk_mul_f32 v[62:63], v[10:11], v[100:101] op_sel_hi:[0,1]
	v_pk_mul_f32 v[64:65], v[10:11], v[94:95] op_sel_hi:[0,1]
	v_pk_mul_f32 v[66:67], v[10:11], v[90:91] op_sel_hi:[0,1]
	v_pk_mul_f32 v[68:69], v[10:11], v[88:89] op_sel_hi:[0,1]
	s_waitcnt vmcnt(0)
; DI void unpack8(u32x4 v, float* f) { f[0] = bflo(v.x); f[1] = bfhi(v.x); f[2] = bflo(v.y); f[3] = bfhi(v.y); f[4] = bflo(v.z); f[5] = bfhi(v.z); f[6] = bflo(v.w); f[7] = bfhi(v.w); }
; DI u32x4 pack8(const float* f) { u32x4 o; o.x = pk2(f[0], f[1]); o.y = pk2(f[2], f[3]); o.z = pk2(f[4], f[5]); o.w = pk2(f[6], f[7]); return o; }
; DI void prep_phase(const KArgs& a, int zz, int e, const bf16_t* Z, const bf16_t* QP, const bf16_t* KVP, bf16_t* Qb, bf16_t* Kb, bf16_t* VT, LAS unsigned char* lds, int G, int bid, int tid, int wave, int lane) {
;     ...
;             const bf16_t* src = QP + (size_t)row * 768 + h * 96;
;             bf16_t* dst = Qb + ((size_t)(b * 8 + h) * TK + pos) * 96;
;             u32x4 qr[12];
; #pragma unroll
;             for (int i = 0; i < 12; ++i) qr[i] = *(const u32x4*)(src + i * 8);
;             float s2 = 0.f;
; #pragma unroll
;             for (int i = 0; i < 12; ++i) { unpack8(qr[i], f);
; #pragma unroll
;                 for (int q = 0; q < 8; ++q) { const float v = f[q] * rs_q; s2 += v * v; } }
;             const float fs = rs_q * rsqrtf(s2 * (1.f / 96.f) + EPS);
; #pragma unroll
;             for (int i = 0; i < 8; ++i) { unpack8(qr[i], f); float o[8];
; #pragma unroll
;                 for (int q = 0; q < 8; ++q) o[q] = f[q] * fs * qn_g[i * 8 + q] * QSCALE;
;                 *(u32x4*)(dst + i * 8) = pack8(o); }
	v_pk_mul_f32 v[62:63], v[180:181], v[62:63]
	s_mov_b32 s4, 0x3e16c740
	v_pk_mul_f32 v[64:65], v[182:183], v[64:65]
	v_pk_mul_f32 v[66:67], v[176:177], v[66:67]
	v_pk_mul_f32 v[68:69], v[178:179], v[68:69]
	v_pk_mul_f32 v[62:63], v[62:63], s[4:5] op_sel_hi:[1,0]
	v_pk_mul_f32 v[64:65], v[64:65], s[4:5] op_sel_hi:[1,0]
	v_pk_mul_f32 v[66:67], v[66:67], s[4:5] op_sel_hi:[1,0]
	v_pk_mul_f32 v[68:69], v[68:69], s[4:5] op_sel_hi:[1,0]
	v_cvt_pk_bf16_f32 v62, v62, v63
	v_cvt_pk_bf16_f32 v63, v64, v65
	v_cvt_pk_bf16_f32 v64, v66, v67
	v_cvt_pk_bf16_f32 v65, v68, v69
	ds_write_b128 v238, v[62:65]
	ds_read_b128 v[62:65], v209 offset:32
	s_nop 0
	ds_read_b128 v[66:69], v209 offset:48
	v_pk_mul_f32 v[30:31], v[10:11], v[30:31] op_sel_hi:[0,1]
	v_pk_mul_f32 v[70:71], v[10:11], v[112:113] op_sel_hi:[0,1]
	v_pk_mul_f32 v[26:27], v[10:11], v[26:27] op_sel_hi:[0,1]
	v_pk_mul_f32 v[24:25], v[10:11], v[24:25] op_sel_hi:[0,1]
	v_pk_mul_f32 v[22:23], v[10:11], v[22:23] op_sel_hi:[0,1]
	v_pk_mul_f32 v[18:19], v[10:11], v[18:19] op_sel_hi:[0,1]
	v_pk_mul_f32 v[16:17], v[10:11], v[16:17] op_sel_hi:[0,1]
	v_pk_mul_f32 v[14:15], v[10:11], v[14:15] op_sel_hi:[0,1]
	v_mov_b32_e32 v44, 1.0
	s_waitcnt lgkmcnt(1)
	v_pk_mul_f32 v[30:31], v[64:65], v[30:31]
	v_pk_mul_f32 v[64:65], v[10:11], v[96:97] op_sel_hi:[0,1]
	s_waitcnt lgkmcnt(0)
	v_pk_mul_f32 v[64:65], v[66:67], v[64:65]
	v_pk_mul_f32 v[66:67], v[10:11], v[92:93] op_sel_hi:[0,1]
	v_pk_mul_f32 v[62:63], v[62:63], v[70:71]
	v_pk_mul_f32 v[66:67], v[68:69], v[66:67]
	v_pk_mul_f32 v[62:63], v[62:63], s[4:5] op_sel_hi:[1,0]
	v_pk_mul_f32 v[30:31], v[30:31], s[4:5] op_sel_hi:[1,0]
	v_pk_mul_f32 v[64:65], v[64:65], s[4:5] op_sel_hi:[1,0]
	v_pk_mul_f32 v[66:67], v[66:67], s[4:5] op_sel_hi:[1,0]
	v_cvt_pk_bf16_f32 v62, v62, v63
	v_cvt_pk_bf16_f32 v63, v30, v31
	v_cvt_pk_bf16_f32 v64, v64, v65
	v_cvt_pk_bf16_f32 v65, v66, v67
	ds_write_b128 v238, v[62:65] offset:16
	ds_read_b128 v[62:65], v209 offset:64
	s_nop 0
	ds_read_b128 v[66:69], v209 offset:80
	v_pk_mul_f32 v[30:31], v[10:11], v[122:123] op_sel_hi:[0,1]
	s_waitcnt lgkmcnt(1)
	v_pk_mul_f32 v[26:27], v[64:65], v[26:27]
	v_pk_mul_f32 v[30:31], v[62:63], v[30:31]
	v_pk_mul_f32 v[62:63], v[26:27], s[4:5] op_sel_hi:[1,0]
	v_pk_mul_f32 v[26:27], v[10:11], v[102:103] op_sel_hi:[0,1]
	s_waitcnt lgkmcnt(0)
	v_pk_mul_f32 v[26:27], v[66:67], v[26:27]
	v_pk_mul_f32 v[30:31], v[30:31], s[4:5] op_sel_hi:[1,0]
	v_pk_mul_f32 v[64:65], v[26:27], s[4:5] op_sel_hi:[1,0]
	v_pk_mul_f32 v[26:27], v[10:11], v[28:29] op_sel_hi:[0,1]
	v_pk_mul_f32 v[26:27], v[68:69], v[26:27]
	v_cvt_pk_bf16_f32 v28, v64, v65
	v_pk_mul_f32 v[66:67], v[26:27], s[4:5] op_sel_hi:[1,0]
	v_cvt_pk_bf16_f32 v26, v30, v31
	v_cvt_pk_bf16_f32 v27, v62, v63
	v_cvt_pk_bf16_f32 v29, v66, v67
	ds_write_b128 v238, v[26:29] offset:32
	ds_read_b128 v[26:29], v209 offset:96
	s_nop 0
	ds_read_b128 v[62:65], v209 offset:112
	v_pk_mul_f32 v[30:31], v[10:11], v[134:135] op_sel_hi:[0,1]
	v_pk_mul_f32 v[66:67], v[10:11], v[120:121] op_sel_hi:[0,1]
	v_pk_mul_f32 v[68:69], v[10:11], v[110:111] op_sel_hi:[0,1]
	s_waitcnt lgkmcnt(1)
	v_pk_mul_f32 v[26:27], v[26:27], v[30:31]
	v_pk_mul_f32 v[28:29], v[28:29], v[66:67]
	s_waitcnt lgkmcnt(0)
	v_pk_mul_f32 v[30:31], v[62:63], v[68:69]
	v_pk_mul_f32 v[24:25], v[64:65], v[24:25]
	v_pk_mul_f32 v[26:27], v[26:27], s[4:5] op_sel_hi:[1,0]
	v_pk_mul_f32 v[28:29], v[28:29], s[4:5] op_sel_hi:[1,0]
	v_pk_mul_f32 v[30:31], v[30:31], s[4:5] op_sel_hi:[1,0]
	v_pk_mul_f32 v[62:63], v[24:25], s[4:5] op_sel_hi:[1,0]
	v_cvt_pk_bf16_f32 v24, v26, v27
	v_cvt_pk_bf16_f32 v25, v28, v29
	v_cvt_pk_bf16_f32 v26, v30, v31
	v_cvt_pk_bf16_f32 v27, v62, v63
	ds_write_b128 v238, v[24:27] offset:48
	ds_read_b128 v[24:27], v209 offset:128
	s_nop 0
	ds_read_b128 v[28:31], v209 offset:144
	v_pk_mul_f32 v[62:63], v[10:11], v[138:139] op_sel_hi:[0,1]
	v_pk_mul_f32 v[64:65], v[10:11], v[126:127] op_sel_hi:[0,1]
	v_pk_mul_f32 v[66:67], v[10:11], v[116:117] op_sel_hi:[0,1]
	s_waitcnt lgkmcnt(1)
	v_pk_mul_f32 v[24:25], v[24:25], v[62:63]
	v_pk_mul_f32 v[26:27], v[26:27], v[64:65]
	s_waitcnt lgkmcnt(0)
	v_pk_mul_f32 v[28:29], v[28:29], v[66:67]
	v_pk_mul_f32 v[22:23], v[30:31], v[22:23]
	v_pk_mul_f32 v[24:25], v[24:25], s[4:5] op_sel_hi:[1,0]
	v_pk_mul_f32 v[26:27], v[26:27], s[4:5] op_sel_hi:[1,0]
	v_pk_mul_f32 v[28:29], v[28:29], s[4:5] op_sel_hi:[1,0]
	v_pk_mul_f32 v[30:31], v[22:23], s[4:5] op_sel_hi:[1,0]
	v_cvt_pk_bf16_f32 v22, v24, v25
	v_cvt_pk_bf16_f32 v23, v26, v27
	v_cvt_pk_bf16_f32 v24, v28, v29
	v_cvt_pk_bf16_f32 v25, v30, v31
	ds_write_b128 v238, v[22:25] offset:64
	ds_read_b128 v[22:25], v209 offset:160
	s_nop 0
	ds_read_b128 v[26:29], v209 offset:176
	v_pk_mul_f32 v[30:31], v[10:11], v[142:143] op_sel_hi:[0,1]
	v_pk_mul_f32 v[62:63], v[10:11], v[130:131] op_sel_hi:[0,1]
	s_waitcnt lgkmcnt(1)
	v_pk_mul_f32 v[22:23], v[22:23], v[30:31]
	v_pk_mul_f32 v[24:25], v[24:25], v[62:63]
	s_waitcnt lgkmcnt(0)
	v_pk_mul_f32 v[18:19], v[26:27], v[18:19]
	v_pk_mul_f32 v[16:17], v[28:29], v[16:17]
	v_pk_mul_f32 v[22:23], v[22:23], s[4:5] op_sel_hi:[1,0]
	v_pk_mul_f32 v[24:25], v[24:25], s[4:5] op_sel_hi:[1,0]
	v_pk_mul_f32 v[18:19], v[18:19], s[4:5] op_sel_hi:[1,0]
	v_pk_mul_f32 v[26:27], v[16:17], s[4:5] op_sel_hi:[1,0]
	v_cvt_pk_bf16_f32 v16, v22, v23
	v_cvt_pk_bf16_f32 v17, v24, v25
	v_cvt_pk_bf16_f32 v18, v18, v19
	v_cvt_pk_bf16_f32 v19, v26, v27
	ds_write_b128 v238, v[16:19] offset:80
	ds_read_b128 v[16:19], v209 offset:192
	s_nop 0
	ds_read_b128 v[22:25], v209 offset:208
	v_pk_mul_f32 v[26:27], v[10:11], v[158:159] op_sel_hi:[0,1]
	v_pk_mul_f32 v[28:29], v[10:11], v[136:137] op_sel_hi:[0,1]
	v_pk_mul_f32 v[30:31], v[10:11], v[128:129] op_sel_hi:[0,1]
	s_waitcnt lgkmcnt(1)
; DI void unpack8(u32x4 v, float* f) { f[0] = bflo(v.x); f[1] = bfhi(v.x); f[2] = bflo(v.y); f[3] = bfhi(v.y); f[4] = bflo(v.z); f[5] = bfhi(v.z); f[6] = bflo(v.w); f[7] = bfhi(v.w); }
; DI u32x4 pack8(const float* f) { u32x4 o; o.x = pk2(f[0], f[1]); o.y = pk2(f[2], f[3]); o.z = pk2(f[4], f[5]); o.w = pk2(f[6], f[7]); return o; }
; DI void prep_phase(const KArgs& a, int zz, int e, const bf16_t* Z, const bf16_t* QP, const bf16_t* KVP, bf16_t* Qb, bf16_t* Kb, bf16_t* VT, LAS unsigned char* lds, int G, int bid, int tid, int wave, int lane) {
;     ...
;             for (int i = 0; i < 8; ++i) { unpack8(qr[i], f); float o[8];
; #pragma unroll
;                 for (int q = 0; q < 8; ++q) o[q] = f[q] * fs * qn_g[i * 8 + q] * QSCALE;
;                 *(u32x4*)(dst + i * 8) = pack8(o); }
; #pragma unroll
;             for (int i = 0; i < 2; ++i) { float f2[8], o1[8], o2[8]; unpack8(qr[8 + i], f); unpack8(qr[10 + i], f2);
; #pragma unroll
;                 for (int q = 0; q < 8; ++q) { const float x1 = f[q] * fs * qn_g[64 + i * 8 + q], x2 = f2[q] * fs * qn_g[80 + i * 8 + q];
;                     float c = 1.f, s = 0.f; if (lat) { const f32x2 cs = taba[t * 16 + i * 8 + q]; c = cs[0]; s = cs[1]; }
;                     o1[q] = (x1 * c - x2 * s) * QSCALE; o2[q] = (x1 * s + x2 * c) * QSCALE; }
;                 *(u32x4*)(dst + 64 + i * 8) = pack8(o1); *(u32x4*)(dst + 80 + i * 8) = pack8(o2); }
	v_pk_mul_f32 v[16:17], v[16:17], v[26:27]
	v_pk_mul_f32 v[18:19], v[18:19], v[28:29]
	s_waitcnt lgkmcnt(0)
	v_pk_mul_f32 v[22:23], v[22:23], v[30:31]
	v_pk_mul_f32 v[14:15], v[24:25], v[14:15]
	v_pk_mul_f32 v[16:17], v[16:17], s[4:5] op_sel_hi:[1,0]
	v_pk_mul_f32 v[18:19], v[18:19], s[4:5] op_sel_hi:[1,0]
	v_pk_mul_f32 v[22:23], v[22:23], s[4:5] op_sel_hi:[1,0]
	v_pk_mul_f32 v[24:25], v[14:15], s[4:5] op_sel_hi:[1,0]
	v_cvt_pk_bf16_f32 v14, v16, v17
	v_cvt_pk_bf16_f32 v15, v18, v19
	v_cvt_pk_bf16_f32 v16, v22, v23
	v_cvt_pk_bf16_f32 v17, v24, v25
	ds_write_b128 v238, v[14:17] offset:96
	ds_read_b128 v[14:17], v209 offset:224
	s_nop 0
	ds_read_b128 v[22:25], v209 offset:240
	v_pk_mul_f32 v[18:19], v[10:11], v[162:163] op_sel_hi:[0,1]
	v_pk_mul_f32 v[26:27], v[10:11], v[140:141] op_sel_hi:[0,1]
	v_pk_mul_f32 v[28:29], v[10:11], v[132:133] op_sel_hi:[0,1]
	v_pk_mul_f32 v[30:31], v[10:11], v[124:125] op_sel_hi:[0,1]
	s_waitcnt lgkmcnt(1)
	v_pk_mul_f32 v[14:15], v[14:15], v[18:19]
	v_pk_mul_f32 v[16:17], v[16:17], v[26:27]
	s_waitcnt lgkmcnt(0)
	v_pk_mul_f32 v[18:19], v[22:23], v[28:29]
	v_pk_mul_f32 v[22:23], v[24:25], v[30:31]
	v_pk_mul_f32 v[14:15], v[14:15], s[4:5] op_sel_hi:[1,0]
	v_pk_mul_f32 v[16:17], v[16:17], s[4:5] op_sel_hi:[1,0]
	v_pk_mul_f32 v[18:19], v[18:19], s[4:5] op_sel_hi:[1,0]
	v_pk_mul_f32 v[22:23], v[22:23], s[4:5] op_sel_hi:[1,0]
	v_cvt_pk_bf16_f32 v14, v14, v15
	v_cvt_pk_bf16_f32 v15, v16, v17
	v_cvt_pk_bf16_f32 v16, v18, v19
	v_cvt_pk_bf16_f32 v17, v22, v23
	ds_write_b128 v238, v[14:17] offset:112
	ds_read_b32 v12, v209 offset:256
	ds_read_b32 v0, v209 offset:320
	v_cmp_gt_f32_e64 s[4:5], s62, v1
	v_mov_b32_e32 v16, 1.0
	s_and_saveexec_b64 s[26:27], vcc
	s_cbranch_execz .LBB0_473
	global_load_dwordx2 v[44:45], v37, s[38:39]
.LBB0_473:
	s_or_b64 exec, exec, s[26:27]
	ds_read_b32 v56, v209 offset:260
	ds_read_b32 v14, v209 offset:324
	v_mov_b32_e32 v19, 0
	v_mov_b32_e32 v17, 0
	s_and_saveexec_b64 s[26:27], vcc
	s_cbranch_execz .LBB0_475
	global_load_dwordx2 v[16:17], v37, s[38:39] offset:8
.LBB0_475:
	s_or_b64 exec, exec, s[26:27]
	ds_read_b32 v64, v209 offset:264
	ds_read_b32 v60, v209 offset:328
	v_mov_b32_e32 v22, 1.0
	v_mov_b32_e32 v18, 1.0
	s_and_saveexec_b64 s[26:27], vcc
	s_cbranch_execz .LBB0_477
	global_load_dwordx2 v[18:19], v37, s[38:39] offset:16
.LBB0_477:
	s_or_b64 exec, exec, s[26:27]
	ds_read_b32 v66, v209 offset:268
	ds_read_b32 v65, v209 offset:332
	v_mov_b32_e32 v25, 0
	v_mov_b32_e32 v23, 0
	s_and_saveexec_b64 s[26:27], vcc
	s_cbranch_execz .LBB0_479
	global_load_dwordx2 v[22:23], v37, s[38:39] offset:24
.LBB0_479:
	s_or_b64 exec, exec, s[26:27]
	ds_read_b32 v68, v209 offset:272
	ds_read_b32 v67, v209 offset:336
	v_mov_b32_e32 v28, 1.0
	v_mov_b32_e32 v24, 1.0
	s_and_saveexec_b64 s[26:27], vcc
	s_cbranch_execz .LBB0_481
	global_load_dwordx2 v[24:25], v37, s[38:39] offset:32
.LBB0_481:
	s_or_b64 exec, exec, s[26:27]
	ds_read_b32 v70, v209 offset:276
	ds_read_b32 v69, v209 offset:340
	v_mov_b32_e32 v31, 0
	v_mov_b32_e32 v29, 0
	s_and_saveexec_b64 s[26:27], vcc
	s_cbranch_execz .LBB0_483
	global_load_dwordx2 v[28:29], v37, s[38:39] offset:40
.LBB0_483:
	s_or_b64 exec, exec, s[26:27]
	ds_read_b32 v72, v209 offset:280
	ds_read_b32 v71, v209 offset:344
	v_mov_b32_e32 v26, 1.0
	v_mov_b32_e32 v30, 1.0
	s_and_saveexec_b64 s[26:27], vcc
	s_cbranch_execz .LBB0_485
	global_load_dwordx2 v[30:31], v37, s[38:39] offset:48
.LBB0_485:
	s_or_b64 exec, exec, s[26:27]
	ds_read_b32 v62, v209 offset:284
	ds_read_b32 v63, v209 offset:348
	v_mov_b32_e32 v15, 0
	v_mov_b32_e32 v27, 0
	s_and_saveexec_b64 s[26:27], vcc
	s_cbranch_execz .LBB0_487
	global_load_dwordx2 v[26:27], v37, s[38:39] offset:56
.LBB0_487:
	s_or_b64 exec, exec, s[26:27]
	v_mul_f32_e32 v61, v10, v61
	v_mul_f32_e32 v57, v10, v57
	s_waitcnt vmcnt(1) lgkmcnt(0)
	v_mul_f32_e32 v61, v61, v71
	v_mul_f32_e32 v57, v57, v72
	v_mul_f32_e32 v71, v61, v31
	v_fma_f32 v71, v57, v30, -v71
	v_mul_f32_e32 v30, v61, v30
	v_mov_b32_e32 v11, v10
	v_fmac_f32_e32 v30, v57, v31
	v_mul_f32_e32 v57, 0x3e16c740, v30
	v_pk_mul_f32 v[30:31], v[10:11], v[58:59]
	v_mul_f32_e32 v58, v10, v174
	v_mul_f32_e32 v54, v10, v54
	v_mul_f32_e32 v58, v58, v69
	v_mul_f32_e32 v54, v54, v70
	v_mul_f32_e32 v59, v58, v29
	v_fma_f32 v59, v54, v28, -v59
	v_mul_f32_e32 v28, v58, v28
	v_fmac_f32_e32 v28, v54, v29
	v_mul_f32_e32 v54, v10, v173
	v_mul_f32_e32 v29, v10, v55
	v_mul_f32_e32 v54, v54, v67
	v_mul_f32_e32 v29, v29, v68
	v_mul_f32_e32 v55, v54, v25
	v_fma_f32 v55, v29, v24, -v55
	v_mul_f32_e32 v24, v54, v24
	v_fmac_f32_e32 v24, v29, v25
	v_mul_f32_e32 v29, v10, v172
	v_mul_f32_e32 v25, v10, v52
	v_mul_f32_e32 v29, v29, v65
	v_mul_f32_e32 v25, v25, v66
	v_mul_f32_e32 v52, v29, v23
	v_fma_f32 v52, v25, v22, -v52
	v_mul_f32_e32 v22, v29, v22
	v_fmac_f32_e32 v22, v25, v23
	v_mul_f32_e32 v25, v10, v171
	v_mul_f32_e32 v23, v10, v53
	v_mul_f32_e32 v25, v25, v60
	v_mul_f32_e32 v23, v23, v64
	v_mul_f32_e32 v29, v25, v19
	v_fma_f32 v29, v23, v18, -v29
	v_mul_f32_e32 v18, v25, v18
	v_fmac_f32_e32 v18, v23, v19
	v_mul_f32_e32 v19, v10, v170
	v_mul_f32_e32 v23, 0x3e16c740, v18
	v_mul_f32_e32 v18, v10, v168
	v_mul_f32_e32 v14, v19, v14
	v_mul_f32_e32 v18, v18, v56
	v_mul_f32_e32 v19, v14, v17
	v_fma_f32 v19, v18, v16, -v19
	v_mul_f32_e32 v14, v14, v16
	v_mul_f32_e32 v16, v10, v167
	v_mul_f32_e32 v12, v12, v16
	v_mul_f32_e32 v16, v10, v169
	v_mul_f32_e32 v0, v0, v16
	v_mul_f32_e32 v16, v0, v45
	s_waitcnt vmcnt(0)
	v_pk_mul_f32 v[30:31], v[30:31], v[62:63]
	v_fma_f32 v16, v12, v44, -v16
	v_fmac_f32_e32 v14, v18, v17
	v_mul_f32_e32 v18, 0x3e16c740, v16
	v_mul_f32_e32 v0, v0, v44
	v_pk_mul_f32 v[16:17], v[30:31], v[26:27]
	v_fmac_f32_e32 v0, v12, v45
	v_sub_f32_e32 v12, v16, v17
	v_pk_mul_f32 v[16:17], v[30:31], v[26:27] op_sel:[0,1] op_sel_hi:[1,0]
	v_mul_f32_e32 v71, 0x3e16c740, v71
	v_mul_f32_e32 v59, 0x3e16c740, v59
	v_mul_f32_e32 v55, 0x3e16c740, v55
	v_mul_f32_e32 v52, 0x3e16c740, v52
	v_mul_f32_e32 v29, 0x3e16c740, v29
	v_mul_f32_e32 v19, 0x3e16c740, v19
	v_mul_f32_e32 v12, 0x3e16c740, v12
	v_add_f32_e32 v16, v16, v17
	v_mul_f32_e32 v28, 0x3e16c740, v28
	v_mul_f32_e32 v24, 0x3e16c740, v24
	v_mul_f32_e32 v22, 0x3e16c740, v22
	v_mul_f32_e32 v14, 0x3e16c740, v14
	v_mul_f32_e32 v0, 0x3e16c740, v0
	v_mul_f32_e32 v25, 0x3e16c740, v16
	v_cvt_pk_bf16_f32 v16, v18, v19
	v_cvt_pk_bf16_f32 v17, v29, v52
	v_cvt_pk_bf16_f32 v18, v55, v59
	v_cvt_pk_bf16_f32 v19, v71, v12
	ds_write_b128 v238, v[16:19] offset:128
	s_nop 1
	v_cvt_pk_bf16_f32 v16, v0, v14
	v_cvt_pk_bf16_f32 v17, v23, v22
	v_cvt_pk_bf16_f32 v18, v24, v28
	v_cvt_pk_bf16_f32 v19, v57, v25
	ds_write_b128 v238, v[16:19] offset:160
	ds_read_b32 v12, v209 offset:288
	ds_read_b32 v0, v209 offset:352
	v_or_b32_e32 v14, 8, v39
	v_mov_b32_e32 v16, 1.0
	v_lshlrev_b32_e32 v110, 3, v14
	v_mov_b32_e32 v14, 1.0
	s_and_saveexec_b64 s[26:27], vcc
	s_cbranch_execz .LBB0_489
	global_load_dwordx2 v[14:15], v110, s[38:39]
; DI void unpack8(u32x4 v, float* f) { f[0] = bflo(v.x); f[1] = bfhi(v.x); f[2] = bflo(v.y); f[3] = bfhi(v.y); f[4] = bflo(v.z); f[5] = bfhi(v.z); f[6] = bflo(v.w); f[7] = bfhi(v.w); }
; DI u32x4 pack8(const float* f) { u32x4 o; o.x = pk2(f[0], f[1]); o.y = pk2(f[2], f[3]); o.z = pk2(f[4], f[5]); o.w = pk2(f[6], f[7]); return o; }
; DI void prep_phase(const KArgs& a, int zz, int e, const bf16_t* Z, const bf16_t* QP, const bf16_t* KVP, bf16_t* Qb, bf16_t* Kb, bf16_t* VT, LAS unsigned char* lds, int G, int bid, int tid, int wave, int lane) {
;     ...
; #pragma unroll
;             for (int i = 0; i < 2; ++i) { float f2[8], o1[8], o2[8]; unpack8(qr[8 + i], f); unpack8(qr[10 + i], f2);
; #pragma unroll
;                 for (int q = 0; q < 8; ++q) { const float x1 = f[q] * fs * qn_g[64 + i * 8 + q], x2 = f2[q] * fs * qn_g[80 + i * 8 + q];
;                     float c = 1.f, s = 0.f; if (lat) { const f32x2 cs = taba[t * 16 + i * 8 + q]; c = cs[0]; s = cs[1]; }
;                     o1[q] = (x1 * c - x2 * s) * QSCALE; o2[q] = (x1 * s + x2 * c) * QSCALE; }
;                 *(u32x4*)(dst + 64 + i * 8) = pack8(o1); *(u32x4*)(dst + 80 + i * 8) = pack8(o2); }
;         }
;         {
;             const bf16_t* src = KVP + (size_t)row * 1024 + h * 128;
;             const bf16_t* kr = zr + 384;
;             bf16_t* dst = Kb + ((size_t)(b * 8 + h) * TK + pos) * 96;
;             u32x4 kn[8], kq[4];
; #pragma unroll
;             for (int i = 0; i < 8; ++i) kn[i] = *(const u32x4*)(src + i * 8);
; #pragma unroll
;             for (int i = 0; i < 4; ++i) kq[i] = *(const u32x4*)(kr + i * 8);
.LBB0_489:
	s_or_b64 exec, exec, s[26:27]
	ds_read_b32 v39, v209 offset:292
	ds_read_b32 v26, v209 offset:356
	v_mov_b32_e32 v19, 0
	v_mov_b32_e32 v17, 0
	s_and_saveexec_b64 s[26:27], vcc
	s_cbranch_execz .LBB0_491
	global_load_dwordx2 v[16:17], v37, s[38:39] offset:72
.LBB0_491:
	s_or_b64 exec, exec, s[26:27]
	ds_read_b32 v55, v209 offset:296
	ds_read_b32 v54, v209 offset:360
	v_mov_b32_e32 v22, 1.0
	v_mov_b32_e32 v18, 1.0
	s_and_saveexec_b64 s[26:27], vcc
	s_cbranch_execz .LBB0_493
	global_load_dwordx2 v[18:19], v37, s[38:39] offset:80
.LBB0_493:
	s_or_b64 exec, exec, s[26:27]
	ds_read_b32 v57, v209 offset:300
	ds_read_b32 v56, v209 offset:364
	v_mov_b32_e32 v25, 0
	v_mov_b32_e32 v23, 0
	s_and_saveexec_b64 s[26:27], vcc
	s_cbranch_execz .LBB0_495
	global_load_dwordx2 v[22:23], v37, s[38:39] offset:88
.LBB0_495:
	s_or_b64 exec, exec, s[26:27]
	ds_read_b32 v59, v209 offset:304
	ds_read_b32 v58, v209 offset:368
	v_mov_b32_e32 v30, 1.0
	v_mov_b32_e32 v24, 1.0
	s_and_saveexec_b64 s[26:27], vcc
	s_cbranch_execz .LBB0_497
	global_load_dwordx2 v[24:25], v37, s[38:39] offset:96
.LBB0_497:
	s_or_b64 exec, exec, s[26:27]
	ds_read_b32 v61, v209 offset:308
	ds_read_b32 v60, v209 offset:372
	v_mov_b32_e32 v45, 0
	v_mov_b32_e32 v31, 0
	s_and_saveexec_b64 s[26:27], vcc
	s_cbranch_execz .LBB0_499
	global_load_dwordx2 v[30:31], v37, s[38:39] offset:104
.LBB0_499:
	s_or_b64 exec, exec, s[26:27]
	ds_read_b32 v63, v209 offset:312
	ds_read_b32 v62, v209 offset:376
	v_mov_b32_e32 v28, 1.0
	v_mov_b32_e32 v44, 1.0
	s_and_saveexec_b64 s[26:27], vcc
	s_cbranch_execz .LBB0_501
	global_load_dwordx2 v[44:45], v37, s[38:39] offset:112
.LBB0_501:
	s_or_b64 exec, exec, s[26:27]
	ds_read_b32 v52, v209 offset:316
	ds_read_b32 v53, v209 offset:380
	v_mov_b32_e32 v27, 0
	v_mov_b32_e32 v29, 0
	s_and_saveexec_b64 s[26:27], vcc
	s_cbranch_execz .LBB0_503
	global_load_dwordx2 v[28:29], v37, s[38:39] offset:120
.LBB0_503:
	s_or_b64 exec, exec, s[26:27]
	v_mul_f32_e32 v13, v10, v13
	v_mul_f32_e32 v4, v10, v4
	v_mul_f32_e32 v64, v10, v166
	s_waitcnt vmcnt(1) lgkmcnt(0)
	v_mul_f32_e32 v13, v13, v62
	v_mul_f32_e32 v42, v10, v42
	v_mul_f32_e32 v26, v4, v26
	v_mul_f32_e32 v63, v64, v63
	v_mul_f32_e32 v62, v13, v45
	v_mul_f32_e32 v13, v13, v44
	v_mul_f32_e32 v8, v10, v8
	v_mul_f32_e32 v39, v42, v39
	v_mul_f32_e32 v4, v26, v17
	v_fma_f32 v62, v63, v44, -v62
	v_fmac_f32_e32 v13, v63, v45
	v_pk_mul_f32 v[44:45], v[10:11], v[50:51]
	v_mul_f32_e32 v11, v10, v48
	v_mul_f32_e32 v8, v8, v60
	v_fma_f32 v4, v39, v16, -v4
	s_waitcnt vmcnt(0)
	v_pk_mul_f32 v[50:51], v[44:45], v[52:53]
	v_mul_f32_e32 v11, v11, v61
	v_mul_f32_e32 v44, v8, v31
	v_mul_f32_e32 v8, v8, v30
	v_mul_f32_e32 v42, 0x3e16c740, v4
	v_mul_f32_e32 v4, v10, v43
	v_fmac_f32_e32 v8, v11, v31
	v_mul_f32_e32 v9, v10, v9
	v_mul_f32_e32 v6, v10, v6
	v_mul_f32_e32 v7, v10, v7
	v_mul_f32_e32 v12, v4, v12
	v_mul_f32_e32 v4, v10, v5
	v_fma_f32 v44, v11, v30, -v44
	v_mul_f32_e32 v11, 0x3e16c740, v8
	v_mul_f32_e32 v8, v10, v49
	v_mul_f32_e32 v9, v9, v58
	v_mul_f32_e32 v31, v10, v46
	v_mul_f32_e32 v46, v6, v56
	v_mul_f32_e32 v45, v10, v47
	v_mul_f32_e32 v48, v7, v54
	v_mul_f32_e32 v0, v4, v0
	v_mul_f32_e32 v8, v8, v59
	v_mul_f32_e32 v30, v9, v25
	v_mul_f32_e32 v31, v31, v57
	v_mul_f32_e32 v6, v46, v23
	v_mul_f32_e32 v47, v45, v55
	v_mul_f32_e32 v7, v48, v19
	v_mul_f32_e32 v4, v0, v15
	v_mul_f32_e32 v9, v9, v24
	v_fma_f32 v30, v8, v24, -v30
	v_fma_f32 v6, v31, v22, -v6
	v_fma_f32 v7, v47, v18, -v7
	v_fma_f32 v4, v12, v14, -v4
	v_fmac_f32_e32 v9, v8, v25
	v_mul_f32_e32 v8, v46, v22
	v_mul_f32_e32 v44, 0x3e16c740, v44
	v_mul_f32_e32 v30, 0x3e16c740, v30
	v_mul_f32_e32 v6, 0x3e16c740, v6
	v_mul_f32_e32 v7, 0x3e16c740, v7
	v_mul_f32_e32 v10, 0x3e16c740, v4
	v_pk_mul_f32 v[4:5], v[50:51], v[28:29]
	v_fmac_f32_e32 v8, v31, v23
	v_sub_f32_e32 v4, v4, v5
	v_cvt_pk_bf16_f32 v5, v7, v6
	v_cvt_pk_bf16_f32 v6, v30, v44
	v_mul_f32_e32 v30, 0x3e16c740, v8
	v_mul_f32_e32 v8, v48, v18
	v_fmac_f32_e32 v8, v47, v19
	v_mul_f32_e32 v18, 0x3e16c740, v8
	v_mul_f32_e32 v8, v26, v16
	v_fmac_f32_e32 v8, v39, v17
	v_mul_f32_e32 v43, 0x3e16c740, v4
	v_cvt_pk_bf16_f32 v4, v10, v42
	v_mul_f32_e32 v10, 0x3e16c740, v9
	v_mul_f32_e32 v16, 0x3e16c740, v8
	v_mul_f32_e32 v0, v0, v14
	v_pk_mul_f32 v[8:9], v[50:51], v[28:29] op_sel:[0,1] op_sel_hi:[1,0]
	v_mul_f32_e32 v62, 0x3e16c740, v62
	v_fmac_f32_e32 v0, v12, v15
	v_add_f32_e32 v8, v8, v9
	v_mul_f32_e32 v13, 0x3e16c740, v13
	v_cvt_pk_bf16_f32 v7, v62, v43
	v_mul_f32_e32 v0, 0x3e16c740, v0
	v_mul_f32_e32 v12, 0x3e16c740, v8
	ds_write_b128 v238, v[4:7] offset:144
	v_cvt_pk_bf16_f32 v8, v0, v16
	v_cvt_pk_bf16_f32 v9, v18, v30
	v_cvt_pk_bf16_f32 v10, v10, v11
	v_cvt_pk_bf16_f32 v11, v13, v12
	v_ashrrev_i32_e32 v39, 31, v38
	global_load_dwordx4 v[4:7], v[40:41], off offset:784
	global_load_dwordx4 v[42:45], v[40:41], off offset:768
	global_load_dwordx4 v[22:25], v[40:41], off offset:800
	v_mul_f32_e32 v0, 0x4b800000, v1
	ds_write_b128 v238, v[8:11] offset:176
	v_readfirstlane_b32 s98, v2
	v_readfirstlane_b32 s99, v3
	v_lshlrev_b64 v[2:3], 11, v[38:39]
	v_lshl_add_u64 v[2:3], v[34:35], 0, v[2:3]
	global_load_dwordx4 v[50:53], v[40:41], off offset:816
	global_load_dwordx4 v[58:61], v[2:3], off
	global_load_dwordx4 v[66:69], v[2:3], off offset:16
	global_load_dwordx4 v[86:89], v[2:3], off offset:48
	global_load_dwordx4 v[74:77], v[2:3], off offset:32
	global_load_dwordx4 v[8:11], v[2:3], off offset:112
	global_load_dwordx4 v[12:15], v[2:3], off offset:96
	global_load_dwordx4 v[16:19], v[2:3], off offset:80
	global_load_dwordx4 v[94:97], v[2:3], off offset:64
	s_waitcnt lgkmcnt(0)
; DI void prep_phase(const KArgs& a, int zz, int e, const bf16_t* Z, const bf16_t* QP, const bf16_t* KVP, bf16_t* Qb, bf16_t* Kb, bf16_t* VT, LAS unsigned char* lds, int G, int bid, int tid, int wave, int lane) {
;     ...
;             bf16_t* dst = Qb + ((size_t)(b * 8 + h) * TK + pos) * 96;
;             u32x4 qr[12];
; #pragma unroll
;             for (int i = 0; i < 12; ++i) qr[i] = *(const u32x4*)(src + i * 8);
;             float s2 = 0.f;
; #pragma unroll
;             for (int i = 0; i < 12; ++i) { unpack8(qr[i], f);
; #pragma unroll
;                 for (int q = 0; q < 8; ++q) { const float v = f[q] * rs_q; s2 += v * v; } }
;             const float fs = rs_q * rsqrtf(s2 * (1.f / 96.f) + EPS);
; #pragma unroll
;             for (int i = 0; i < 8; ++i) { unpack8(qr[i], f); float o[8];
; #pragma unroll
;                 for (int q = 0; q < 8; ++q) o[q] = f[q] * fs * qn_g[i * 8 + q] * QSCALE;
;                 *(u32x4*)(dst + i * 8) = pack8(o); }
; #pragma unroll
;             for (int i = 0; i < 2; ++i) { float f2[8], o1[8], o2[8]; unpack8(qr[8 + i], f); unpack8(qr[10 + i], f2);
; #pragma unroll
;                 for (int q = 0; q < 8; ++q) { const float x1 = f[q] * fs * qn_g[64 + i * 8 + q], x2 = f2[q] * fs * qn_g[80 + i * 8 + q];
;                     float c = 1.f, s = 0.f; if (lat) { const f32x2 cs = taba[t * 16 + i * 8 + q]; c = cs[0]; s = cs[1]; }
;                     o1[q] = (x1 * c - x2 * s) * QSCALE; o2[q] = (x1 * s + x2 * c) * QSCALE; }
;                 *(u32x4*)(dst + 64 + i * 8) = pack8(o1); *(u32x4*)(dst + 80 + i * 8) = pack8(o2); }
;         }
;         {
;             const bf16_t* src = KVP + (size_t)row * 1024 + h * 128;
;             const bf16_t* kr = zr + 384;
;             bf16_t* dst = Kb + ((size_t)(b * 8 + h) * TK + pos) * 96;
;             u32x4 kn[8], kq[4];
; #pragma unroll
;             for (int i = 0; i < 8; ++i) kn[i] = *(const u32x4*)(src + i * 8);
; #pragma unroll
;             for (int i = 0; i < 4; ++i) kq[i] = *(const u32x4*)(kr + i * 8);
;             float s2 = 0.f;
; #pragma unroll
;             for (int i = 0; i < 8; ++i) { unpack8(kn[i], f);
; #pragma unroll
;                 for (int q = 0; q < 8; ++q) { const float v = f[q] * rs_kv; s2 += v * v; } }
; #pragma unroll
;             for (int i = 0; i < 4; ++i) { unpack8(kq[i], f);
; #pragma unroll
;                 for (int q = 0; q < 8; ++q) s2 += f[q] * f[q]; }
	ds_read_b128 v[184:187], v239
	ds_read_b128 v[188:191], v240
	ds_read_b128 v[192:195], v241
	ds_read_b128 v[196:199], v239 offset:3104
	ds_read_b128 v[200:203], v240 offset:3104
	ds_read_b128 v[204:207], v241 offset:3104
	ds_read_b128 v[214:217], v239 offset:6208
	ds_read_b128 v[218:221], v240 offset:6208
	ds_read_b128 v[222:225], v241 offset:6208
	ds_read_b128 v[226:229], v239 offset:9312
	ds_read_b128 v[230:233], v240 offset:9312
	ds_read_b128 v[234:237], v241 offset:9312
	s_waitcnt lgkmcnt(9)
	global_store_dwordx4 v242, v[184:187], s[98:99]
	global_store_dwordx4 v243, v[188:191], s[98:99]
	global_store_dwordx4 v244, v[192:195], s[98:99]
	s_add_u32 s98, s98, 0x198000
	s_addc_u32 s99, s99, 0
	s_waitcnt lgkmcnt(6)
	global_store_dwordx4 v242, v[196:199], s[98:99]
	global_store_dwordx4 v243, v[200:203], s[98:99]
	global_store_dwordx4 v244, v[204:207], s[98:99]
	s_add_u32 s98, s98, 0x198000
	s_addc_u32 s99, s99, 0
	s_waitcnt lgkmcnt(3)
	global_store_dwordx4 v242, v[214:217], s[98:99]
	global_store_dwordx4 v243, v[218:221], s[98:99]
	global_store_dwordx4 v244, v[222:225], s[98:99]
	s_add_u32 s98, s98, 0x198000
	s_addc_u32 s99, s99, 0
	s_waitcnt lgkmcnt(0)
	global_store_dwordx4 v242, v[226:229], s[98:99]
	global_store_dwordx4 v243, v[230:233], s[98:99]
	global_store_dwordx4 v244, v[234:237], s[98:99]
	v_cndmask_b32_e64 v0, v1, v0, s[4:5]
	v_rsq_f32_e32 v0, v0
	s_waitcnt vmcnt(23)
	v_lshlrev_b32_e32 v111, 16, v4
	v_mul_f32_e32 v1, 0x45800000, v0
	v_cndmask_b32_e64 v26, v0, v1, s[4:5]
	s_waitcnt vmcnt(22)
	v_lshlrev_b32_e32 v125, 16, v44
	v_and_b32_e32 v127, 0xffff0000, v44
	v_lshlrev_b32_e32 v130, 16, v45
	v_and_b32_e32 v40, 0xffff0000, v45
	s_waitcnt vmcnt(19)
	v_and_b32_e32 v65, 0xffff0000, v58
	v_lshlrev_b32_e32 v64, 16, v58
	v_mul_f32_e32 v71, v26, v65
	v_lshlrev_b32_e32 v31, 16, v53
	v_and_b32_e32 v28, 0xffff0000, v52
	v_lshlrev_b32_e32 v29, 16, v52
	v_and_b32_e32 v39, 0xffff0000, v53
	v_lshlrev_b32_e32 v52, 16, v60
	v_and_b32_e32 v53, 0xffff0000, v60
	v_lshlrev_b32_e32 v60, 16, v59
	v_mul_f32_e32 v58, v26, v64
	v_mul_f32_e32 v131, v71, v71
	v_lshlrev_b32_e32 v44, 16, v61
	v_and_b32_e32 v45, 0xffff0000, v61
	v_and_b32_e32 v61, 0xffff0000, v59
	v_mul_f32_e32 v59, v26, v60
	v_fmac_f32_e32 v131, v58, v58
	v_mul_f32_e32 v70, v26, v61
	v_fmac_f32_e32 v131, v59, v59
	v_mul_f32_e32 v62, v26, v52
	v_fmac_f32_e32 v131, v70, v70
	v_and_b32_e32 v41, 0xffff0000, v25
	v_mov_b32_e32 v30, v39
	v_mul_f32_e32 v63, v26, v53
	v_fmac_f32_e32 v131, v62, v62
	v_lshlrev_b32_e32 v118, 16, v42
	v_and_b32_e32 v119, 0xffff0000, v42
	v_lshlrev_b32_e32 v121, 16, v43
	v_and_b32_e32 v123, 0xffff0000, v43
	v_lshlrev_b32_e32 v43, 16, v25
	v_mov_b32_e32 v42, v41
	v_pk_mul_f32 v[56:57], v[30:31], v[30:31]
	v_mul_f32_e32 v30, v26, v44
	v_fmac_f32_e32 v131, v63, v63
	v_pk_mul_f32 v[46:47], v[42:43], v[42:43]
	v_mul_f32_e32 v42, v26, v45
	v_fmac_f32_e32 v131, v30, v30
	s_waitcnt vmcnt(18)
	v_lshlrev_b32_e32 v72, 16, v66
	v_fmac_f32_e32 v131, v42, v42
	v_and_b32_e32 v73, 0xffff0000, v66
	v_mul_f32_e32 v66, v26, v72
	v_lshlrev_b32_e32 v62, 16, v68
	v_and_b32_e32 v63, 0xffff0000, v68
	v_lshlrev_b32_e32 v68, 16, v67
	v_mul_f32_e32 v79, v26, v73
	v_fmac_f32_e32 v131, v66, v66
	v_lshlrev_b32_e32 v58, 16, v69
	v_and_b32_e32 v59, 0xffff0000, v69
	v_and_b32_e32 v69, 0xffff0000, v67
	v_mul_f32_e32 v67, v26, v68
	v_fmac_f32_e32 v131, v79, v79
	v_mul_f32_e32 v78, v26, v69
	v_fmac_f32_e32 v131, v67, v67
	v_mul_f32_e32 v70, v26, v62
	v_fmac_f32_e32 v131, v78, v78
	v_mul_f32_e32 v71, v26, v63
	v_fmac_f32_e32 v131, v70, v70
	v_mul_f32_e32 v30, v26, v58
	v_fmac_f32_e32 v131, v71, v71
	v_mul_f32_e32 v42, v26, v59
	v_fmac_f32_e32 v131, v30, v30
	s_waitcnt vmcnt(16)
	v_lshlrev_b32_e32 v82, 16, v74
	v_fmac_f32_e32 v131, v42, v42
	v_and_b32_e32 v83, 0xffff0000, v74
	v_mul_f32_e32 v74, v26, v82
	v_lshlrev_b32_e32 v70, 16, v76
	v_and_b32_e32 v71, 0xffff0000, v76
	v_lshlrev_b32_e32 v76, 16, v75
	v_mul_f32_e32 v81, v26, v83
	v_fmac_f32_e32 v131, v74, v74
	v_lshlrev_b32_e32 v66, 16, v77
	v_and_b32_e32 v67, 0xffff0000, v77
	v_and_b32_e32 v77, 0xffff0000, v75
	v_mul_f32_e32 v75, v26, v76
	v_fmac_f32_e32 v131, v81, v81
	v_mul_f32_e32 v80, v26, v77
	v_fmac_f32_e32 v131, v75, v75
	v_mul_f32_e32 v78, v26, v70
	v_fmac_f32_e32 v131, v80, v80
	v_mul_f32_e32 v79, v26, v71
	v_fmac_f32_e32 v131, v78, v78
	v_mul_f32_e32 v30, v26, v66
	v_fmac_f32_e32 v131, v79, v79
	v_mul_f32_e32 v42, v26, v67
	v_fmac_f32_e32 v131, v30, v30
	v_lshlrev_b32_e32 v92, 16, v86
	v_fmac_f32_e32 v131, v42, v42
	v_and_b32_e32 v93, 0xffff0000, v86
	v_mul_f32_e32 v86, v26, v92
	v_lshlrev_b32_e32 v74, 16, v89
	v_and_b32_e32 v75, 0xffff0000, v89
	v_lshlrev_b32_e32 v84, 16, v87
	v_mul_f32_e32 v89, v26, v93
	v_fmac_f32_e32 v131, v86, v86
	v_and_b32_e32 v85, 0xffff0000, v87
	v_mul_f32_e32 v87, v26, v84
	v_fmac_f32_e32 v131, v89, v89
	v_lshlrev_b32_e32 v78, 16, v88
	v_and_b32_e32 v79, 0xffff0000, v88
	v_mul_f32_e32 v88, v26, v85
	v_fmac_f32_e32 v131, v87, v87
	v_and_b32_e32 v112, 0xffff0000, v4
	v_lshlrev_b32_e32 v113, 16, v5
	v_and_b32_e32 v114, 0xffff0000, v5
	v_lshlrev_b32_e32 v115, 16, v6
	v_and_b32_e32 v116, 0xffff0000, v6
	v_lshlrev_b32_e32 v117, 16, v7
	v_and_b32_e32 v38, 0xffff0000, v7
	global_load_dwordx4 v[0:3], v149, s[42:43] offset:16
	global_load_dwordx4 v[4:7], v149, s[42:43]
	v_mul_f32_e32 v80, v26, v78
	v_fmac_f32_e32 v131, v88, v88
	v_mul_f32_e32 v81, v26, v79
	v_fmac_f32_e32 v131, v80, v80
	v_mul_f32_e32 v30, v26, v74
	v_fmac_f32_e32 v131, v81, v81
	v_mul_f32_e32 v42, v26, v75
	v_fmac_f32_e32 v131, v30, v30
	s_waitcnt vmcnt(14)
; DI void unpack8(u32x4 v, float* f) { f[0] = bflo(v.x); f[1] = bfhi(v.x); f[2] = bflo(v.y); f[3] = bfhi(v.y); f[4] = bflo(v.z); f[5] = bfhi(v.z); f[6] = bflo(v.w); f[7] = bfhi(v.w); }
; DI u32x4 pack8(const float* f) { u32x4 o; o.x = pk2(f[0], f[1]); o.y = pk2(f[2], f[3]); o.z = pk2(f[4], f[5]); o.w = pk2(f[6], f[7]); return o; }
; DI void prep_phase(const KArgs& a, int zz, int e, const bf16_t* Z, const bf16_t* QP, const bf16_t* KVP, bf16_t* Qb, bf16_t* Kb, bf16_t* VT, LAS unsigned char* lds, int G, int bid, int tid, int wave, int lane) {
;     ...
;             float s2 = 0.f;
; #pragma unroll
;             for (int i = 0; i < 8; ++i) { unpack8(kn[i], f);
; #pragma unroll
;                 for (int q = 0; q < 8; ++q) { const float v = f[q] * rs_kv; s2 += v * v; } }
; #pragma unroll
;             for (int i = 0; i < 4; ++i) { unpack8(kq[i], f);
; #pragma unroll
;                 for (int q = 0; q < 8; ++q) s2 += f[q] * f[q]; }
;             const float ks = rsqrtf(s2 * (1.f / 96.f) + EPS);
;             const float fs = rs_kv * ks;
; #pragma unroll
;             for (int i = 0; i < 8; ++i) { unpack8(kn[i], f); float o[8];
; #pragma unroll
;                 for (int q = 0; q < 8; ++q) o[q] = f[q] * fs * kn_g[i * 8 + q];
;                 *(u32x4*)(dst + i * 8) = pack8(o); }
	v_lshlrev_b32_e32 v86, 16, v96
	v_and_b32_e32 v87, 0xffff0000, v96
	v_lshlrev_b32_e32 v96, 16, v94
	v_fmac_f32_e32 v131, v42, v42
	v_lshlrev_b32_e32 v80, 16, v97
	v_and_b32_e32 v81, 0xffff0000, v97
	v_and_b32_e32 v97, 0xffff0000, v94
	v_mul_f32_e32 v94, v26, v96
	v_lshlrev_b32_e32 v90, 16, v95
	v_mul_f32_e32 v99, v26, v97
	v_fmac_f32_e32 v131, v94, v94
	v_and_b32_e32 v91, 0xffff0000, v95
	v_mul_f32_e32 v95, v26, v90
	v_fmac_f32_e32 v131, v99, v99
	v_mul_f32_e32 v98, v26, v91
	v_fmac_f32_e32 v131, v95, v95
	v_mul_f32_e32 v88, v26, v86
	v_fmac_f32_e32 v131, v98, v98
	v_mul_f32_e32 v89, v26, v87
	v_fmac_f32_e32 v131, v88, v88
	v_mul_f32_e32 v30, v26, v80
	v_fmac_f32_e32 v131, v89, v89
	v_mul_f32_e32 v42, v26, v81
	v_fmac_f32_e32 v131, v30, v30
	v_lshlrev_b32_e32 v100, 16, v16
	v_fmac_f32_e32 v131, v42, v42
	v_and_b32_e32 v101, 0xffff0000, v16
	v_mul_f32_e32 v16, v26, v100
	v_lshlrev_b32_e32 v94, 16, v18
	v_and_b32_e32 v95, 0xffff0000, v18
	v_lshlrev_b32_e32 v18, 16, v17
	v_mul_f32_e32 v103, v26, v101
	v_fmac_f32_e32 v131, v16, v16
	v_lshlrev_b32_e32 v88, 16, v19
	v_and_b32_e32 v89, 0xffff0000, v19
	v_and_b32_e32 v19, 0xffff0000, v17
	v_mul_f32_e32 v17, v26, v18
	v_fmac_f32_e32 v131, v103, v103
	v_mul_f32_e32 v102, v26, v19
	v_fmac_f32_e32 v131, v17, v17
	v_mul_f32_e32 v98, v26, v94
	v_fmac_f32_e32 v131, v102, v102
	v_mul_f32_e32 v99, v26, v95
	v_fmac_f32_e32 v131, v98, v98
	v_mul_f32_e32 v30, v26, v88
	v_fmac_f32_e32 v131, v99, v99
	v_mul_f32_e32 v42, v26, v89
	v_fmac_f32_e32 v131, v30, v30
	v_lshlrev_b32_e32 v106, 16, v12
	v_fmac_f32_e32 v131, v42, v42
	v_and_b32_e32 v107, 0xffff0000, v12
	v_mul_f32_e32 v12, v26, v106
	v_lshlrev_b32_e32 v98, 16, v14
	v_and_b32_e32 v99, 0xffff0000, v14
	v_lshlrev_b32_e32 v14, 16, v13
	v_mul_f32_e32 v105, v26, v107
	v_fmac_f32_e32 v131, v12, v12
	v_lshlrev_b32_e32 v16, 16, v15
	v_and_b32_e32 v17, 0xffff0000, v15
	v_and_b32_e32 v15, 0xffff0000, v13
	v_mul_f32_e32 v13, v26, v14
	v_fmac_f32_e32 v131, v105, v105
	v_mul_f32_e32 v104, v26, v15
	v_fmac_f32_e32 v131, v13, v13
	v_mul_f32_e32 v102, v26, v98
	v_fmac_f32_e32 v131, v104, v104
	v_mul_f32_e32 v103, v26, v99
	v_fmac_f32_e32 v131, v102, v102
	v_mul_f32_e32 v30, v26, v16
	v_fmac_f32_e32 v131, v103, v103
	v_mul_f32_e32 v42, v26, v17
	v_fmac_f32_e32 v131, v30, v30
	v_lshlrev_b32_e32 v108, 16, v8
	v_fmac_f32_e32 v131, v42, v42
	v_and_b32_e32 v109, 0xffff0000, v8
	v_mul_f32_e32 v8, v26, v108
	v_lshlrev_b32_e32 v104, 16, v9
	v_mul_f32_e32 v133, v26, v109
	v_fmac_f32_e32 v131, v8, v8
	v_and_b32_e32 v105, 0xffff0000, v9
	v_mul_f32_e32 v9, v26, v104
	v_fmac_f32_e32 v131, v133, v133
	v_lshlrev_b32_e32 v102, 16, v10
	v_mul_f32_e32 v132, v26, v105
	v_fmac_f32_e32 v131, v9, v9
	v_and_b32_e32 v103, 0xffff0000, v10
	v_mul_f32_e32 v10, v26, v102
	v_fmac_f32_e32 v131, v132, v132
	v_lshlrev_b32_e32 v12, 16, v11
	v_mul_f32_e32 v42, v26, v103
	v_fmac_f32_e32 v131, v10, v10
	v_and_b32_e32 v13, 0xffff0000, v11
	v_mul_f32_e32 v11, v26, v12
	v_fmac_f32_e32 v131, v42, v42
	v_mul_f32_e32 v30, v26, v13
	v_fmac_f32_e32 v131, v11, v11
	v_fmac_f32_e32 v131, v30, v30
	v_fmac_f32_e32 v131, v118, v118
	v_fmac_f32_e32 v131, v119, v119
	v_fmac_f32_e32 v131, v121, v121
	v_fmac_f32_e32 v131, v123, v123
	v_fmac_f32_e32 v131, v125, v125
	v_fmac_f32_e32 v131, v127, v127
	v_fmac_f32_e32 v131, v130, v130
	v_fmac_f32_e32 v131, v40, v40
	v_fmac_f32_e32 v131, v111, v111
	v_fmac_f32_e32 v131, v112, v112
	v_fmac_f32_e32 v131, v113, v113
	v_fmac_f32_e32 v131, v114, v114
	v_fmac_f32_e32 v131, v115, v115
	v_fmac_f32_e32 v131, v116, v116
	v_fmac_f32_e32 v131, v117, v117
	v_lshlrev_b32_e32 v120, 16, v22
	v_fmac_f32_e32 v131, v38, v38
	v_and_b32_e32 v122, 0xffff0000, v22
	v_fmac_f32_e32 v131, v120, v120
	v_lshlrev_b32_e32 v124, 16, v23
	v_fmac_f32_e32 v131, v122, v122
	v_and_b32_e32 v126, 0xffff0000, v23
	v_fmac_f32_e32 v131, v124, v124
	v_lshlrev_b32_e32 v128, 16, v24
	v_fmac_f32_e32 v131, v126, v126
	v_and_b32_e32 v129, 0xffff0000, v24
	v_fmac_f32_e32 v131, v128, v128
	v_fmac_f32_e32 v131, v129, v129
	v_and_b32_e32 v22, 0xffff0000, v50
	v_lshlrev_b32_e32 v23, 16, v50
	v_add_f32_e32 v8, v47, v131
	v_pk_mul_f32 v[48:49], v[22:23], v[22:23]
	v_add_f32_e32 v8, v46, v8
	v_and_b32_e32 v24, 0xffff0000, v51
	v_lshlrev_b32_e32 v25, 16, v51
	v_add_f32_e32 v8, v49, v8
	v_pk_mul_f32 v[50:51], v[24:25], v[24:25]
	v_add_f32_e32 v8, v48, v8
	v_add_f32_e32 v8, v51, v8
	v_pk_mul_f32 v[54:55], v[28:29], v[28:29]
	v_add_f32_e32 v8, v50, v8
	v_add_f32_e32 v8, v55, v8
	v_add_f32_e32 v8, v54, v8
	v_add_f32_e32 v8, v57, v8
	v_add_f32_e32 v8, v56, v8
	v_fmamk_f32 v8, v8, 0x3c2aaaab, v150
	v_mul_f32_e32 v9, 0x4b800000, v8
	v_cmp_gt_f32_e64 s[4:5], s62, v8
	s_nop 1
	v_cndmask_b32_e64 v8, v8, v9, s[4:5]
	v_rsq_f32_e32 v10, v8
	v_lshl_add_u64 v[8:9], v[20:21], 1, s[8:9]
	v_mul_f32_e32 v11, 0x45800000, v10
	v_cndmask_b32_e64 v10, v10, v11, s[4:5]
	v_mul_f32_e32 v20, v26, v10
	v_pk_mul_f32 v[46:47], v[20:21], v[64:65] op_sel_hi:[0,1]
	s_waitcnt vmcnt(0)
	v_pk_mul_f32 v[4:5], v[4:5], v[46:47]
	v_pk_mul_f32 v[46:47], v[20:21], v[60:61] op_sel_hi:[0,1]
	v_pk_mul_f32 v[6:7], v[6:7], v[46:47]
	v_pk_mul_f32 v[46:47], v[20:21], v[52:53] op_sel_hi:[0,1]
	v_pk_mul_f32 v[46:47], v[0:1], v[46:47]
	v_pk_mul_f32 v[0:1], v[20:21], v[44:45] op_sel_hi:[0,1]
	v_pk_mul_f32 v[44:45], v[2:3], v[0:1]
	v_cvt_pk_bf16_f32 v0, v4, v5
	v_cvt_pk_bf16_f32 v1, v6, v7
	v_cvt_pk_bf16_f32 v2, v46, v47
	v_cvt_pk_bf16_f32 v3, v44, v45
	ds_write_b128 v238, v[0:3]
	ds_read_b128 v[0:3], v209 offset:416
	s_nop 0
	ds_read_b128 v[4:7], v209 offset:432
	v_pk_mul_f32 v[44:45], v[20:21], v[72:73] op_sel_hi:[0,1]
	v_pk_mul_f32 v[46:47], v[20:21], v[84:85] op_sel_hi:[0,1]
	v_pk_mul_f32 v[48:49], v[20:21], v[78:79] op_sel_hi:[0,1]
	v_pk_mul_f32 v[50:51], v[20:21], v[74:75] op_sel_hi:[0,1]
	v_pk_mul_f32 v[18:19], v[20:21], v[18:19] op_sel_hi:[0,1]
	v_pk_mul_f32 v[14:15], v[20:21], v[14:15] op_sel_hi:[0,1]
	v_pk_mul_f32 v[16:17], v[20:21], v[16:17] op_sel_hi:[0,1]
	v_pk_mul_f32 v[12:13], v[20:21], v[12:13] op_sel_hi:[0,1]
	v_mov_b32_e32 v26, 1.0
	s_waitcnt lgkmcnt(1)
; DI void unpack8(u32x4 v, float* f) { f[0] = bflo(v.x); f[1] = bfhi(v.x); f[2] = bflo(v.y); f[3] = bfhi(v.y); f[4] = bflo(v.z); f[5] = bfhi(v.z); f[6] = bflo(v.w); f[7] = bfhi(v.w); }
; DI u32x4 pack8(const float* f) { u32x4 o; o.x = pk2(f[0], f[1]); o.y = pk2(f[2], f[3]); o.z = pk2(f[4], f[5]); o.w = pk2(f[6], f[7]); return o; }
; DI void prep_phase(const KArgs& a, int zz, int e, const bf16_t* Z, const bf16_t* QP, const bf16_t* KVP, bf16_t* Qb, bf16_t* Kb, bf16_t* VT, LAS unsigned char* lds, int G, int bid, int tid, int wave, int lane) {
;     ...
;             for (int i = 0; i < 8; ++i) { unpack8(kn[i], f); float o[8];
; #pragma unroll
;                 for (int q = 0; q < 8; ++q) o[q] = f[q] * fs * kn_g[i * 8 + q];
;                 *(u32x4*)(dst + i * 8) = pack8(o); }
; #pragma unroll
;             for (int i = 0; i < 2; ++i) { float f2[8], o1[8], o2[8]; unpack8(kq[i], f); unpack8(kq[2 + i], f2);
; #pragma unroll
;                 for (int q = 0; q < 8; ++q) { const float x1 = f[q] * ks * kn_g[64 + i * 8 + q], x2 = f2[q] * ks * kn_g[80 + i * 8 + q];
;                     float c = 1.f, s = 0.f; if (lat) { const f32x2 cs = taba[t * 16 + i * 8 + q]; c = cs[0]; s = cs[1]; }
;                     o1[q] = x1 * c - x2 * s; o2[q] = x1 * s + x2 * c; }
;                 *(u32x4*)(dst + 64 + i * 8) = pack8(o1); *(u32x4*)(dst + 80 + i * 8) = pack8(o2); }
	v_pk_mul_f32 v[0:1], v[0:1], v[44:45]
	v_pk_mul_f32 v[44:45], v[20:21], v[68:69] op_sel_hi:[0,1]
	v_pk_mul_f32 v[2:3], v[2:3], v[44:45]
	v_pk_mul_f32 v[44:45], v[20:21], v[62:63] op_sel_hi:[0,1]
	s_waitcnt lgkmcnt(0)
	v_pk_mul_f32 v[4:5], v[4:5], v[44:45]
	v_pk_mul_f32 v[44:45], v[20:21], v[58:59] op_sel_hi:[0,1]
	v_pk_mul_f32 v[6:7], v[6:7], v[44:45]
	v_cvt_pk_bf16_f32 v0, v0, v1
	v_cvt_pk_bf16_f32 v1, v2, v3
	v_cvt_pk_bf16_f32 v2, v4, v5
	v_cvt_pk_bf16_f32 v3, v6, v7
	ds_write_b128 v238, v[0:3] offset:16
	ds_read_b128 v[0:3], v209 offset:448
	s_nop 0
	ds_read_b128 v[4:7], v209 offset:464
	v_pk_mul_f32 v[44:45], v[20:21], v[82:83] op_sel_hi:[0,1]
	s_waitcnt lgkmcnt(1)
	v_pk_mul_f32 v[0:1], v[0:1], v[44:45]
	v_pk_mul_f32 v[44:45], v[20:21], v[76:77] op_sel_hi:[0,1]
	v_pk_mul_f32 v[2:3], v[2:3], v[44:45]
	v_pk_mul_f32 v[44:45], v[20:21], v[70:71] op_sel_hi:[0,1]
	s_waitcnt lgkmcnt(0)
	v_pk_mul_f32 v[4:5], v[4:5], v[44:45]
	v_pk_mul_f32 v[44:45], v[20:21], v[66:67] op_sel_hi:[0,1]
	v_pk_mul_f32 v[6:7], v[6:7], v[44:45]
	v_cvt_pk_bf16_f32 v0, v0, v1
	v_cvt_pk_bf16_f32 v1, v2, v3
	v_cvt_pk_bf16_f32 v2, v4, v5
	v_cvt_pk_bf16_f32 v3, v6, v7
	ds_write_b128 v238, v[0:3] offset:32
	ds_read_b128 v[0:3], v209 offset:480
	s_nop 0
	ds_read_b128 v[4:7], v209 offset:496
	v_pk_mul_f32 v[44:45], v[20:21], v[92:93] op_sel_hi:[0,1]
	s_waitcnt lgkmcnt(1)
	v_pk_mul_f32 v[0:1], v[0:1], v[44:45]
	v_pk_mul_f32 v[2:3], v[2:3], v[46:47]
	s_waitcnt lgkmcnt(0)
	v_pk_mul_f32 v[4:5], v[4:5], v[48:49]
	v_pk_mul_f32 v[6:7], v[6:7], v[50:51]
	v_cvt_pk_bf16_f32 v0, v0, v1
	v_cvt_pk_bf16_f32 v1, v2, v3
	v_cvt_pk_bf16_f32 v2, v4, v5
	v_cvt_pk_bf16_f32 v3, v6, v7
	ds_write_b128 v238, v[0:3] offset:48
	ds_read_b128 v[0:3], v209 offset:512
	s_nop 0
	ds_read_b128 v[4:7], v209 offset:528
	v_pk_mul_f32 v[44:45], v[20:21], v[96:97] op_sel_hi:[0,1]
	v_pk_mul_f32 v[46:47], v[20:21], v[90:91] op_sel_hi:[0,1]
	v_pk_mul_f32 v[48:49], v[20:21], v[86:87] op_sel_hi:[0,1]
	v_pk_mul_f32 v[50:51], v[20:21], v[80:81] op_sel_hi:[0,1]
	s_waitcnt lgkmcnt(1)
	v_pk_mul_f32 v[0:1], v[0:1], v[44:45]
	v_pk_mul_f32 v[2:3], v[2:3], v[46:47]
	s_waitcnt lgkmcnt(0)
	v_pk_mul_f32 v[4:5], v[4:5], v[48:49]
	v_pk_mul_f32 v[6:7], v[6:7], v[50:51]
	v_cvt_pk_bf16_f32 v0, v0, v1
	v_cvt_pk_bf16_f32 v1, v2, v3
	v_cvt_pk_bf16_f32 v2, v4, v5
	v_cvt_pk_bf16_f32 v3, v6, v7
	ds_write_b128 v238, v[0:3] offset:64
	ds_read_b128 v[0:3], v209 offset:544
	s_nop 0
	ds_read_b128 v[4:7], v209 offset:560
	v_pk_mul_f32 v[44:45], v[20:21], v[100:101] op_sel_hi:[0,1]
	v_pk_mul_f32 v[46:47], v[20:21], v[94:95] op_sel_hi:[0,1]
	v_pk_mul_f32 v[48:49], v[20:21], v[88:89] op_sel_hi:[0,1]
	s_waitcnt lgkmcnt(1)
	v_pk_mul_f32 v[0:1], v[0:1], v[44:45]
	v_pk_mul_f32 v[2:3], v[2:3], v[18:19]
	s_waitcnt lgkmcnt(0)
	v_pk_mul_f32 v[4:5], v[4:5], v[46:47]
	v_pk_mul_f32 v[6:7], v[6:7], v[48:49]
	v_cvt_pk_bf16_f32 v0, v0, v1
	v_cvt_pk_bf16_f32 v1, v2, v3
	v_cvt_pk_bf16_f32 v2, v4, v5
	v_cvt_pk_bf16_f32 v3, v6, v7
	ds_write_b128 v238, v[0:3] offset:80
	ds_read_b128 v[0:3], v209 offset:576
	s_nop 0
	ds_read_b128 v[4:7], v209 offset:592
	v_pk_mul_f32 v[18:19], v[20:21], v[106:107] op_sel_hi:[0,1]
	v_pk_mul_f32 v[44:45], v[20:21], v[98:99] op_sel_hi:[0,1]
	s_waitcnt lgkmcnt(1)
	v_pk_mul_f32 v[0:1], v[0:1], v[18:19]
	v_pk_mul_f32 v[2:3], v[2:3], v[14:15]
	s_waitcnt lgkmcnt(0)
	v_pk_mul_f32 v[4:5], v[4:5], v[44:45]
	v_pk_mul_f32 v[6:7], v[6:7], v[16:17]
	v_cvt_pk_bf16_f32 v0, v0, v1
	v_cvt_pk_bf16_f32 v1, v2, v3
	v_cvt_pk_bf16_f32 v2, v4, v5
	v_cvt_pk_bf16_f32 v3, v6, v7
	ds_write_b128 v238, v[0:3] offset:96
	ds_read_b128 v[0:3], v209 offset:608
	s_nop 0
	ds_read_b128 v[4:7], v209 offset:624
	v_pk_mul_f32 v[14:15], v[20:21], v[108:109] op_sel_hi:[0,1]
	v_pk_mul_f32 v[16:17], v[20:21], v[104:105] op_sel_hi:[0,1]
	v_pk_mul_f32 v[18:19], v[20:21], v[102:103] op_sel_hi:[0,1]
	s_waitcnt lgkmcnt(1)
	v_pk_mul_f32 v[0:1], v[0:1], v[14:15]
	v_pk_mul_f32 v[2:3], v[2:3], v[16:17]
	s_waitcnt lgkmcnt(0)
	v_pk_mul_f32 v[4:5], v[4:5], v[18:19]
	v_pk_mul_f32 v[6:7], v[6:7], v[12:13]
	v_cvt_pk_bf16_f32 v0, v0, v1
	v_cvt_pk_bf16_f32 v1, v2, v3
	v_cvt_pk_bf16_f32 v2, v4, v5
	v_cvt_pk_bf16_f32 v3, v6, v7
	ds_write_b128 v238, v[0:3] offset:112
	ds_read_b32 v11, v209 offset:640
	s_nop 0
	ds_read_b32 v0, v209 offset:704
	v_mov_b32_e32 v2, 1.0
	s_and_saveexec_b64 s[4:5], vcc
	s_cbranch_execz .LBB0_505
	global_load_dwordx2 v[26:27], v37, s[38:39]
.LBB0_505:
	s_or_b64 exec, exec, s[4:5]
	ds_read_b32 v42, v209 offset:644
	ds_read_b32 v30, v209 offset:708
	v_mov_b32_e32 v5, 0
	v_mov_b32_e32 v3, 0
	s_and_saveexec_b64 s[4:5], vcc
	s_cbranch_execz .LBB0_507
	global_load_dwordx2 v[2:3], v37, s[38:39] offset:8
.LBB0_507:
	s_or_b64 exec, exec, s[4:5]
	ds_read_b32 v45, v209 offset:648
	ds_read_b32 v44, v209 offset:712
	v_mov_b32_e32 v6, 1.0
	v_mov_b32_e32 v4, 1.0
	s_and_saveexec_b64 s[4:5], vcc
	s_cbranch_execz .LBB0_509
	global_load_dwordx2 v[4:5], v37, s[38:39] offset:16
.LBB0_509:
	s_or_b64 exec, exec, s[4:5]
	ds_read_b32 v47, v209 offset:652
	ds_read_b32 v46, v209 offset:716
	v_mov_b32_e32 v13, 0
	v_mov_b32_e32 v7, 0
	s_and_saveexec_b64 s[4:5], vcc
	s_cbranch_execz .LBB0_511
	global_load_dwordx2 v[6:7], v37, s[38:39] offset:24
.LBB0_511:
	s_or_b64 exec, exec, s[4:5]
	ds_read_b32 v49, v209 offset:656
	ds_read_b32 v48, v209 offset:720
	v_mov_b32_e32 v16, 1.0
	v_mov_b32_e32 v12, 1.0
	s_and_saveexec_b64 s[4:5], vcc
	s_cbranch_execz .LBB0_513
	global_load_dwordx2 v[12:13], v37, s[38:39] offset:32
.LBB0_513:
	s_or_b64 exec, exec, s[4:5]
	ds_read_b32 v51, v209 offset:660
	ds_read_b32 v50, v209 offset:724
	v_mov_b32_e32 v19, 0
	v_mov_b32_e32 v17, 0
	s_and_saveexec_b64 s[4:5], vcc
	s_cbranch_execz .LBB0_515
	global_load_dwordx2 v[16:17], v37, s[38:39] offset:40
; #define LAS __attribute__((address_space(3)))
; DI void unpack8(u32x4 v, float* f) { f[0] = bflo(v.x); f[1] = bfhi(v.x); f[2] = bflo(v.y); f[3] = bfhi(v.y); f[4] = bflo(v.z); f[5] = bfhi(v.z); f[6] = bflo(v.w); f[7] = bfhi(v.w); }
; DI u32x4 pack8(const float* f) { u32x4 o; o.x = pk2(f[0], f[1]); o.y = pk2(f[2], f[3]); o.z = pk2(f[4], f[5]); o.w = pk2(f[6], f[7]); return o; }
; DI void prep_phase(const KArgs& a, int zz, int e, const bf16_t* Z, const bf16_t* QP, const bf16_t* KVP, bf16_t* Qb, bf16_t* Kb, bf16_t* VT, LAS unsigned char* lds, int G, int bid, int tid, int wave, int lane) {
;     ...
; #pragma unroll
;             for (int i = 0; i < 2; ++i) { float f2[8], o1[8], o2[8]; unpack8(kq[i], f); unpack8(kq[2 + i], f2);
; #pragma unroll
;                 for (int q = 0; q < 8; ++q) { const float x1 = f[q] * ks * kn_g[64 + i * 8 + q], x2 = f2[q] * ks * kn_g[80 + i * 8 + q];
;                     float c = 1.f, s = 0.f; if (lat) { const f32x2 cs = taba[t * 16 + i * 8 + q]; c = cs[0]; s = cs[1]; }
;                     o1[q] = x1 * c - x2 * s; o2[q] = x1 * s + x2 * c; }
;                 *(u32x4*)(dst + 64 + i * 8) = pack8(o1); *(u32x4*)(dst + 80 + i * 8) = pack8(o2); }
;         }
;     }
;     {
;         const int gw = bid * 8 + wave, NGW = G * 8;
;         LAS bf16_t* tl = (LAS bf16_t*)(lds + wave * 8704);
;         for (int u = (gw + NGW / 2) % NGW; u < (M / 64) * 2; u += NGW) {
;             const int rb = u >> 1, hh = (u & 1) * 4; const int row = rb * 64 + lane, rowb = rb * 64;
;             int b, posb;
;             if (rowb < ML) { b = rowb >> 12; posb = TC + (rowb & 4095); } else { const int rc = rowb - ML; b = rc >> 8; posb = rc & 255; }
.LBB0_515:
	s_or_b64 exec, exec, s[4:5]
	ds_read_b32 v53, v209 offset:664
	ds_read_b32 v52, v209 offset:728
	v_mov_b32_e32 v14, 1.0
	v_mov_b32_e32 v18, 1.0
	s_and_saveexec_b64 s[4:5], vcc
	s_cbranch_execz .LBB0_517
	global_load_dwordx2 v[18:19], v37, s[38:39] offset:48
.LBB0_517:
	s_or_b64 exec, exec, s[4:5]
	ds_read_b32 v20, v209 offset:668
	ds_read_b32 v21, v209 offset:732
	v_mov_b32_e32 v1, 0
	v_mov_b32_e32 v15, 0
	s_and_saveexec_b64 s[4:5], vcc
	s_cbranch_execz .LBB0_519
	global_load_dwordx2 v[14:15], v37, s[38:39] offset:56
.LBB0_519:
	s_or_b64 exec, exec, s[4:5]
	v_mul_f32_e32 v43, v10, v43
	v_mul_f32_e32 v54, v10, v130
	s_waitcnt vmcnt(1) lgkmcnt(0)
	v_mul_f32_e32 v43, v43, v52
	v_mul_f32_e32 v53, v54, v53
	v_mul_f32_e32 v52, v43, v19
	v_fma_f32 v52, v53, v18, -v52
	v_mul_f32_e32 v53, v53, v19
	v_fmac_f32_e32 v53, v43, v18
	v_pk_mul_f32 v[18:19], v[10:11], v[40:41] op_sel_hi:[0,1]
	s_waitcnt vmcnt(0)
	v_pk_mul_f32 v[18:19], v[18:19], v[20:21]
	v_mul_f32_e32 v21, v10, v129
	v_mul_f32_e32 v20, v10, v127
	v_mul_f32_e32 v21, v21, v50
	v_mul_f32_e32 v20, v20, v51
	v_mul_f32_e32 v40, v21, v17
	v_fma_f32 v40, v20, v16, -v40
	v_mul_f32_e32 v17, v20, v17
	v_mul_f32_e32 v20, v10, v128
	v_fmac_f32_e32 v17, v21, v16
	v_mul_f32_e32 v16, v10, v125
	v_mul_f32_e32 v20, v20, v48
	v_mul_f32_e32 v16, v16, v49
	v_mul_f32_e32 v21, v20, v13
	v_fma_f32 v21, v16, v12, -v21
	v_mul_f32_e32 v13, v16, v13
	v_mul_f32_e32 v16, v10, v126
	v_fmac_f32_e32 v13, v20, v12
	v_mul_f32_e32 v12, v10, v123
	v_mul_f32_e32 v16, v16, v46
	v_mul_f32_e32 v12, v12, v47
	v_mul_f32_e32 v20, v16, v7
	v_fma_f32 v20, v12, v6, -v20
	v_mul_f32_e32 v12, v12, v7
	v_fmac_f32_e32 v12, v16, v6
	v_mul_f32_e32 v6, v10, v121
	v_mul_f32_e32 v7, v10, v124
	v_mul_f32_e32 v6, v6, v45
	v_mul_f32_e32 v7, v7, v44
	v_mul_f32_e32 v16, v7, v5
	v_mul_f32_e32 v41, v6, v5
	v_fma_f32 v16, v6, v4, -v16
	v_fmac_f32_e32 v41, v7, v4
	v_mul_f32_e32 v4, v10, v119
	v_mul_f32_e32 v5, v10, v122
	v_mul_f32_e32 v4, v4, v42
	v_mul_f32_e32 v5, v5, v30
	v_mul_f32_e32 v6, v5, v3
	v_mul_f32_e32 v42, v4, v3
	v_fma_f32 v30, v4, v2, -v6
	v_fmac_f32_e32 v42, v5, v2
	v_mul_f32_e32 v2, v10, v118
	v_mul_f32_e32 v2, v11, v2
	v_mul_f32_e32 v3, v10, v120
	v_mul_f32_e32 v0, v0, v3
	v_mul_f32_e32 v11, v2, v27
	v_mul_f32_e32 v3, v0, v27
	v_fmac_f32_e32 v11, v0, v26
	v_mul_f32_e32 v0, v18, v14
	v_fma_f32 v3, v2, v26, -v3
	v_pk_fma_f32 v[4:5], v[18:19], v[14:15], v[0:1] op_sel_hi:[1,1,0] neg_lo:[1,0,0] neg_hi:[1,0,0]
	v_mul_f32_e32 v0, v19, v14
	v_pk_fma_f32 v[6:7], v[18:19], v[14:15], v[0:1] op_sel:[1,0,0] op_sel_hi:[0,1,0]
	v_cvt_pk_bf16_f32 v2, v3, v30
	v_cvt_pk_bf16_f32 v3, v16, v20
	v_cvt_pk_bf16_f32 v4, v21, v40
	v_cvt_pk_bf16_f32 v5, v52, v5
	ds_write_b128 v238, v[2:5] offset:128
	v_mov_b32_e32 v0, 1.0
	s_nop 0
	v_cvt_pk_bf16_f32 v2, v11, v42
	v_cvt_pk_bf16_f32 v3, v41, v12
	v_cvt_pk_bf16_f32 v4, v13, v17
	v_cvt_pk_bf16_f32 v5, v53, v7
	ds_write_b128 v238, v[2:5] offset:160
	ds_read_b32 v27, v209 offset:672
	ds_read_b32 v26, v209 offset:736
	v_mov_b32_e32 v2, 1.0
	s_and_saveexec_b64 s[4:5], vcc
	s_cbranch_execz .LBB0_521
	global_load_dwordx2 v[0:1], v110, s[38:39]
.LBB0_521:
	s_or_b64 exec, exec, s[4:5]
	ds_read_b32 v40, v209 offset:676
	ds_read_b32 v30, v209 offset:740
	v_mov_b32_e32 v5, 0
	v_mov_b32_e32 v3, 0
	s_and_saveexec_b64 s[4:5], vcc
	s_cbranch_execz .LBB0_523
	global_load_dwordx2 v[2:3], v37, s[38:39] offset:72
.LBB0_523:
	s_or_b64 exec, exec, s[4:5]
	ds_read_b32 v42, v209 offset:680
	ds_read_b32 v41, v209 offset:744
	v_mov_b32_e32 v6, 1.0
	v_mov_b32_e32 v4, 1.0
	s_and_saveexec_b64 s[4:5], vcc
	s_cbranch_execz .LBB0_525
	global_load_dwordx2 v[4:5], v37, s[38:39] offset:80
.LBB0_525:
	s_or_b64 exec, exec, s[4:5]
	ds_read_b32 v44, v209 offset:684
	ds_read_b32 v43, v209 offset:748
	v_mov_b32_e32 v13, 0
	v_mov_b32_e32 v7, 0
	s_and_saveexec_b64 s[4:5], vcc
	s_cbranch_execz .LBB0_527
	global_load_dwordx2 v[6:7], v37, s[38:39] offset:88
.LBB0_527:
	s_or_b64 exec, exec, s[4:5]
	ds_read_b32 v46, v209 offset:688
	ds_read_b32 v45, v209 offset:752
	v_mov_b32_e32 v16, 1.0
	v_mov_b32_e32 v12, 1.0
	s_and_saveexec_b64 s[4:5], vcc
	s_cbranch_execz .LBB0_529
	global_load_dwordx2 v[12:13], v37, s[38:39] offset:96
.LBB0_529:
	s_or_b64 exec, exec, s[4:5]
	ds_read_b32 v48, v209 offset:692
	ds_read_b32 v47, v209 offset:756
	v_mov_b32_e32 v19, 0
	v_mov_b32_e32 v17, 0
	s_and_saveexec_b64 s[4:5], vcc
	s_cbranch_execz .LBB0_531
	global_load_dwordx2 v[16:17], v37, s[38:39] offset:104
.LBB0_531:
	s_or_b64 exec, exec, s[4:5]
	ds_read_b32 v50, v209 offset:696
	ds_read_b32 v49, v209 offset:760
	v_mov_b32_e32 v14, 1.0
	v_mov_b32_e32 v18, 1.0
	s_and_saveexec_b64 s[4:5], vcc
	s_cbranch_execz .LBB0_533
	global_load_dwordx2 v[18:19], v37, s[38:39] offset:112
.LBB0_533:
	s_or_b64 exec, exec, s[4:5]
	ds_read_b32 v20, v209 offset:700
	ds_read_b32 v21, v209 offset:764
	v_mov_b32_e32 v15, 0
	s_and_saveexec_b64 s[4:5], vcc
	s_cbranch_execz .LBB0_466
	global_load_dwordx2 v[14:15], v37, s[38:39] offset:120
	s_branch .LBB0_466
.LBB0_535:
	s_or_b64 exec, exec, s[0:1]
	s_barrier
	s_abs_i32 s1, s48
	s_waitcnt vmcnt(5)
	v_cvt_f32_u32_e32 v0, s1
	s_sub_i32 s5, 0, s1
	s_lshl_b32 s0, s33, 2
	s_add_i32 s4, s36, s0
	v_rcp_iflag_f32_e32 v0, v0
	s_ashr_i32 s0, s4, 31
	s_abs_i32 s4, s4
	v_mul_f32_e32 v0, 0x4f7ffffe, v0
	v_cvt_u32_f32_e32 v0, v0
	s_nop 0
	v_readfirstlane_b32 s6, v0
	s_mul_i32 s5, s5, s6
	s_mul_hi_u32 s5, s6, s5
	s_add_i32 s6, s6, s5
	s_mul_hi_u32 s5, s4, s6
	s_mul_i32 s5, s5, s1
	s_sub_i32 s4, s4, s5
	s_sub_i32 s5, s4, s1
	s_cmp_ge_u32 s4, s1
	s_cselect_b32 s4, s5, s4
	s_sub_i32 s5, s4, s1
	s_cmp_ge_u32 s4, s1
	s_cselect_b32 s1, s5, s4
	s_xor_b32 s1, s1, s0
	s_sub_i32 s6, s1, s0
	s_cmpk_gt_i32 s6, 0x87f
	s_cbranch_scc1 .LBB0_544
	s_add_u32 s7, s84, 0x3abdc000
	s_mul_i32 s4, s37, 0x2200
	s_addc_u32 s8, s85, 0
	s_add_i32 s4, s4, 0
	v_mov_b32_e32 v0, s4
	s_movk_i32 s4, 0x88
	s_lshl_b32 s9, s6, 2
	v_mad_u32_u24 v18, v152, s4, v0
	s_movk_i32 s4, 0xff7a
	s_and_b32 s23, s9, 4
	v_mad_i32_i24 v19, v152, s4, v18
	s_add_i32 s23, s23, 4
	s_lshl_b32 s24, s33, 5
	v_readlane_b32 s4, v254, 24
	s_add_u32 s25, s4, s78
	v_readlane_b32 s4, v254, 25
	s_addc_u32 s26, s4, s79
	s_lshl_b32 s1, s1, 5
	s_lshl_b32 s0, s0, 5
	s_sub_i32 s27, s1, s0
	s_lshl_b32 s38, s33, 8

; #define LAS __attribute__((address_space(3)))
; __global__ void __launch_bounds__(NTHREADS) fwd_kernel(KArgs a) {
;     extern __shared__ __attribute__((aligned(16))) unsigned char lds_raw[];
;     LAS unsigned char* lds = (LAS unsigned char*)lds_raw;
;     cg::grid_group grid = cg::this_grid();
;     volatile LAS unsigned* bst = (volatile LAS unsigned*)(lds + 133120);
;     if (threadIdx.x == 0) { bst[0] = 0u; bst[1] = 0u; }
;     __syncthreads();
;     XcdBarrier xbar = xcd_barrier_post((unsigned*)(a.ws + OFF_BAR), bst);
;     { const int tid = threadIdx.x, lane = tid & 63, wave = __builtin_amdgcn_readfirstlane(tid >> 6);
;       if (EN(0)) phase0(a, lds, gridDim.x, blockIdx.x, tid, wave, lane); }
;     if (a.ws == nullptr) grid.sync();
;     xcd_barrier(xbar);
;     for (int step = 0; step < 34; ++step) {
;         int zz = 0; asm volatile("" : "+s"(zz));
;         int tid = threadIdx.x; asm volatile("" : "+v"(tid));
;         int G = gridDim.x, bid = blockIdx.x; asm volatile("" : "+s"(G), "+s"(bid));
;         const int lane = tid & 63, wave = __builtin_amdgcn_readfirstlane(tid >> 6);
	.amdhsa_kernel _Z10fwd_kernel5KArgs
		.amdhsa_group_segment_fixed_size 18432
		.amdhsa_private_segment_fixed_size 0
		.amdhsa_kernarg_size 560
		.amdhsa_user_sgpr_count 2
		.amdhsa_user_sgpr_dispatch_ptr 0
		.amdhsa_user_sgpr_queue_ptr 0
		.amdhsa_user_sgpr_kernarg_segment_ptr 1
		.amdhsa_user_sgpr_dispatch_id 0
		.amdhsa_user_sgpr_kernarg_preload_length 0
		.amdhsa_user_sgpr_kernarg_preload_offset 0
		.amdhsa_user_sgpr_private_segment_size 0
		.amdhsa_uses_dynamic_stack 0
		.amdhsa_enable_private_segment 0
		.amdhsa_system_sgpr_workgroup_id_x 1
		.amdhsa_system_sgpr_workgroup_id_y 0
		.amdhsa_system_sgpr_workgroup_id_z 0
		.amdhsa_system_sgpr_workgroup_info 0
		.amdhsa_system_vgpr_workitem_id 2
		.amdhsa_next_free_vgpr 256
		.amdhsa_next_free_sgpr 102
		.amdhsa_accum_offset 256
		.amdhsa_reserve_vcc 1
		.amdhsa_float_round_mode_32 0
		.amdhsa_float_round_mode_16_64 0
		.amdhsa_float_denorm_mode_32 3
		.amdhsa_float_denorm_mode_16_64 3
		.amdhsa_dx10_clamp 1
		.amdhsa_ieee_mode 1
		.amdhsa_fp16_overflow 0
		.amdhsa_tg_split 0
		.amdhsa_exception_fp_ieee_invalid_op 0
		.amdhsa_exception_fp_denorm_src 0
		.amdhsa_exception_fp_ieee_div_zero 0
		.amdhsa_exception_fp_ieee_overflow 0
		.amdhsa_exception_fp_ieee_underflow 0
		.amdhsa_exception_fp_ieee_inexact 0
		.amdhsa_exception_int_div_zero 0
	.end_amdhsa_kernel

; __global__ void __launch_bounds__(NTHREADS) fwd_kernel(KArgs a) {
;     extern __shared__ __attribute__((aligned(16))) unsigned char lds_raw[];
amdhsa.kernels:
  - .agpr_count:     0
    .args:
      - .offset:         0
        .size:           304
        .value_kind:     by_value
      - .offset:         304
        .size:           4
        .value_kind:     hidden_block_count_x
      - .offset:         308
        .size:           4
        .value_kind:     hidden_block_count_y
      - .offset:         312
        .size:           4
        .value_kind:     hidden_block_count_z
      - .offset:         316
        .size:           2
        .value_kind:     hidden_group_size_x
      - .offset:         318
        .size:           2
        .value_kind:     hidden_group_size_y
      - .offset:         320
        .size:           2
        .value_kind:     hidden_group_size_z
      - .offset:         322
        .size:           2
        .value_kind:     hidden_remainder_x
      - .offset:         324
        .size:           2
        .value_kind:     hidden_remainder_y
      - .offset:         326
        .size:           2
        .value_kind:     hidden_remainder_z
      - .offset:         344
        .size:           8
        .value_kind:     hidden_global_offset_x
      - .offset:         352
        .size:           8
        .value_kind:     hidden_global_offset_y
      - .offset:         360
        .size:           8
        .value_kind:     hidden_global_offset_z
      - .offset:         368
        .size:           2
        .value_kind:     hidden_grid_dims
      - .offset:         392
        .size:           8
        .value_kind:     hidden_multigrid_sync_arg
      - .offset:         424
        .size:           4
        .value_kind:     hidden_dynamic_lds_size
    .group_segment_fixed_size: 18432
    .kernarg_segment_align: 8
    .kernarg_segment_size: 560
    .language:       OpenCL C
    .language_version:
      - 2
      - 0
    .max_flat_workgroup_size: 512
    .name:           _Z10fwd_kernel5KArgs
    .private_segment_fixed_size: 0
    .sgpr_count:     108
    .sgpr_spill_count: 188
    .symbol:         _Z10fwd_kernel5KArgs.kd
    .uniform_work_group_size: 1
    .uses_dynamic_stack: false
    .vgpr_count:     256
    .vgpr_spill_count: 0
    .wavefront_size: 64
